# waitcnt cleanup: the redundant s_waitcnt lgkmcnt(0) right after each K-loop barrier (already drained before the barrier) deleted, 28 sites
# baseline (speedup 1.0000x reference)
; #define PG8_STAGE(bufoff, gbase, voff) do { _Pragma("unroll") for (int _i = 0; _i < 2; ++_i) \
;         __builtin_amdgcn_global_load_lds((const unsigned*)((const char*)(gbase) + (voff)[_i]), (LAS unsigned*)(lds + (bufoff) + ldsw + _i * 8192), 16, 0, 0); } while (0)
; #define PG8_LDA(dst, b, h) do { _Pragma("unroll") for (int m = 0; m < 4; ++m) _Pragma("unroll") for (int k = 0; k < 2; ++k) dst[m][k] = *(const LAS bf16x8*)(lds + PG8_SA(b, h) + aoff + m * 2048 + k * 1024); } while (0)
; #define PG8_LDB(dst, b, h) do { _Pragma("unroll") for (int n = 0; n < 2; ++n) _Pragma("unroll") for (int k = 0; k < 2; ++k) dst[n][k] = *(const LAS bf16x8*)(lds + PG8_SB(b, h) + boff + n * 2048 + k * 1024); } while (0)
; #define PG8_WAIT_V(n) asm volatile("s_waitcnt vmcnt(" #n ")" ::: "memory")
; #define PG8_WAIT_L(n) asm volatile("s_waitcnt lgkmcnt(" #n ")" ::: "memory")
; #define PG8_BAR __builtin_amdgcn_s_barrier()
; #define PG8_SCHED __builtin_amdgcn_sched_barrier(0)
; template <class Epi, class Sched, bool I8 = false>
; __device__ __forceinline__ void gemm_phase(LAS unsigned char* lds, const Gemm g, const Sched& S, const Epi& E) {
;     ...
;             PG8_LDB(B0, 0, 0); PG8_LDB(B1, 0, 1); PG8_SCHED; PG8_LDA(At, 0, 0); PG8_STAGE(PG8_SA(1, 1), a1 + hstepA, voffA);
;             PG8_WAIT_V(8); PG8_WAIT_L(0); PG8_BAR; PG8_MMA(0, 0, At, B0); PG8_MMA(0, 1, At, B1); PG8_BAR; PG8_SCHED;
;             PG8_LDA(At, 0, 1); PG8_STAGE(PG8_SB(0, 0), b2, voffB); PG8_STAGE(PG8_SB(0, 1), b2 + hstepB, voffB); PG8_STAGE(PG8_SA(0, 0), a2, voffA);
;             PG8_WAIT_V(8); PG8_WAIT_L(0); PG8_BAR; PG8_MMA(1, 0, At, B0); PG8_MMA(1, 1, At, B1); PG8_BAR; PG8_SCHED;
.LBB0_1169:
	ds_read_b128 v[90:93], v169
	ds_read_b128 v[98:101], v169 offset:1024
	ds_read_b128 v[172:175], v169 offset:2048
	ds_read_b128 v[176:179], v169 offset:3072
	ds_read_b128 v[180:183], v170
	ds_read_b128 v[184:187], v170 offset:1024
	ds_read_b128 v[188:191], v170 offset:2048
	ds_read_b128 v[192:195], v170 offset:3072
	s_add_u32 s22, s20, 0x4000
	s_addc_u32 s23, s21, 0
	s_cmp_eq_u32 s53, 28
	s_cselect_b32 s26, s49, s22
	s_cselect_b32 s27, s13, s23
	s_cselect_b32 s24, s50, s51
	s_cselect_b32 s25, s11, s52
	s_add_u32 s22, s26, 0x8000
	s_addc_u32 s23, s27, 0
	s_sub_u32 s98, s20, 0x4000
	s_subb_u32 s99, s21, 0
	s_mov_b32 m0, s43
	s_nop 0
	global_load_lds_dwordx4 v144, s[98:99]
	s_mov_b32 m0, s44
	s_nop 0
	global_load_lds_dwordx4 v140, s[98:99]
	s_add_i32 m0, s36, 0xc000
	ds_read_b128 v[196:199], v171
	ds_read_b128 v[200:203], v171 offset:1024
	ds_read_b128 v[204:207], v171 offset:2048
	ds_read_b128 v[208:211], v171 offset:3072
	ds_read_b128 v[212:215], v171 offset:4096
	ds_read_b128 v[216:219], v171 offset:5120
	ds_read_b128 v[220:223], v171 offset:6144
	ds_read_b128 v[224:227], v171 offset:7168
	global_load_lds_dwordx4 v148, s[20:21]
	s_add_i32 m0, s36, 0xe000
	s_nop 0
	global_load_lds_dwordx4 v150, s[20:21]
	s_waitcnt vmcnt(8)
	s_waitcnt lgkmcnt(0)
	s_barrier
	v_mfma_i32_16x16x64_i8 v[134:137], v[90:93], v[196:199], v[134:137]
	v_mfma_i32_16x16x64_i8 v[130:133], v[172:175], v[196:199], v[130:133]
	v_mfma_i32_16x16x64_i8 v[118:121], v[90:93], v[204:207], v[118:121]
	v_mfma_i32_16x16x64_i8 v[114:117], v[172:175], v[204:207], v[114:117]
	v_mfma_i32_16x16x64_i8 v[102:105], v[90:93], v[212:215], v[102:105]
	v_mfma_i32_16x16x64_i8 v[94:97], v[172:175], v[212:215], v[94:97]
	v_mfma_i32_16x16x64_i8 v[78:81], v[90:93], v[220:223], v[78:81]
	v_mfma_i32_16x16x64_i8 v[74:77], v[172:175], v[220:223], v[74:77]
	v_mfma_i32_16x16x64_i8 v[134:137], v[98:101], v[200:203], v[134:137]
	v_mfma_i32_16x16x64_i8 v[130:133], v[176:179], v[200:203], v[130:133]
	v_mfma_i32_16x16x64_i8 v[118:121], v[98:101], v[208:211], v[118:121]
	v_mfma_i32_16x16x64_i8 v[114:117], v[176:179], v[208:211], v[114:117]
	v_mfma_i32_16x16x64_i8 v[102:105], v[98:101], v[216:219], v[102:105]
	v_mfma_i32_16x16x64_i8 v[94:97], v[176:179], v[216:219], v[94:97]
	v_mfma_i32_16x16x64_i8 v[78:81], v[98:101], v[224:227], v[78:81]
	v_mfma_i32_16x16x64_i8 v[74:77], v[176:179], v[224:227], v[74:77]
	v_mfma_i32_16x16x64_i8 v[126:129], v[180:183], v[196:199], v[126:129]
	v_mfma_i32_16x16x64_i8 v[122:125], v[188:191], v[196:199], v[122:125]
	v_mfma_i32_16x16x64_i8 v[110:113], v[180:183], v[204:207], v[110:113]
	v_mfma_i32_16x16x64_i8 v[106:109], v[188:191], v[204:207], v[106:109]
	v_mfma_i32_16x16x64_i8 v[86:89], v[180:183], v[212:215], v[86:89]
	v_mfma_i32_16x16x64_i8 v[82:85], v[188:191], v[212:215], v[82:85]
	v_mfma_i32_16x16x64_i8 v[70:73], v[180:183], v[220:223], v[70:73]
	v_mfma_i32_16x16x64_i8 v[66:69], v[188:191], v[220:223], v[66:69]
	v_mfma_i32_16x16x64_i8 v[126:129], v[184:187], v[200:203], v[126:129]
	v_mfma_i32_16x16x64_i8 v[122:125], v[192:195], v[200:203], v[122:125]
	v_mfma_i32_16x16x64_i8 v[110:113], v[184:187], v[208:211], v[110:113]
	v_mfma_i32_16x16x64_i8 v[106:109], v[192:195], v[208:211], v[106:109]
	v_mfma_i32_16x16x64_i8 v[86:89], v[184:187], v[216:219], v[86:89]
	v_mfma_i32_16x16x64_i8 v[82:85], v[192:195], v[216:219], v[82:85]
	v_mfma_i32_16x16x64_i8 v[70:73], v[184:187], v[224:227], v[70:73]
	v_mfma_i32_16x16x64_i8 v[66:69], v[192:195], v[224:227], v[66:69]
	s_barrier
	s_add_i32 s54, s46, s33
	s_mov_b32 m0, s54
	ds_read_b128 v[196:199], v171 offset:16384
	ds_read_b128 v[200:203], v171 offset:17408
	ds_read_b128 v[204:207], v171 offset:18432
	ds_read_b128 v[208:211], v171 offset:19456
	ds_read_b128 v[212:215], v171 offset:20480
	ds_read_b128 v[216:219], v171 offset:21504
	ds_read_b128 v[220:223], v171 offset:22528
	ds_read_b128 v[224:227], v171 offset:23552
	global_load_lds_dwordx4 v142, s[24:25]
	s_add_i32 m0, s54, 0x2000
	s_add_u32 s54, s24, 0x4000
	s_addc_u32 s55, s25, 0
	s_add_i32 s56, s47, s33
	global_load_lds_dwordx4 v138, s[24:25]
	s_mov_b32 m0, s56
	s_nop 0
	global_load_lds_dwordx4 v142, s[54:55]
	s_add_i32 m0, s56, 0x2000
	s_nop 0
	global_load_lds_dwordx4 v138, s[54:55]
	s_waitcnt vmcnt(6)
	s_waitcnt lgkmcnt(0)
	s_barrier
	v_mfma_i32_16x16x64_i8 v[62:65], v[90:93], v[196:199], v[62:65]
	v_mfma_i32_16x16x64_i8 v[58:61], v[172:175], v[196:199], v[58:61]
	v_mfma_i32_16x16x64_i8 v[46:49], v[90:93], v[204:207], v[46:49]
	v_mfma_i32_16x16x64_i8 v[42:45], v[172:175], v[204:207], v[42:45]
	v_mfma_i32_16x16x64_i8 v[30:33], v[90:93], v[212:215], v[30:33]
	v_mfma_i32_16x16x64_i8 v[26:29], v[172:175], v[212:215], v[26:29]
	v_mfma_i32_16x16x64_i8 v[14:17], v[90:93], v[220:223], v[14:17]
	v_mfma_i32_16x16x64_i8 v[10:13], v[172:175], v[220:223], v[10:13]
	v_mfma_i32_16x16x64_i8 v[62:65], v[98:101], v[200:203], v[62:65]
	v_mfma_i32_16x16x64_i8 v[58:61], v[176:179], v[200:203], v[58:61]
	v_mfma_i32_16x16x64_i8 v[46:49], v[98:101], v[208:211], v[46:49]
	v_mfma_i32_16x16x64_i8 v[42:45], v[176:179], v[208:211], v[42:45]
	v_mfma_i32_16x16x64_i8 v[30:33], v[98:101], v[216:219], v[30:33]
	v_mfma_i32_16x16x64_i8 v[26:29], v[176:179], v[216:219], v[26:29]
	v_mfma_i32_16x16x64_i8 v[14:17], v[98:101], v[224:227], v[14:17]
	v_mfma_i32_16x16x64_i8 v[10:13], v[176:179], v[224:227], v[10:13]
	v_mfma_i32_16x16x64_i8 v[54:57], v[180:183], v[196:199], v[54:57]
	v_mfma_i32_16x16x64_i8 v[50:53], v[188:191], v[196:199], v[50:53]
	v_mfma_i32_16x16x64_i8 v[38:41], v[180:183], v[204:207], v[38:41]
	v_mfma_i32_16x16x64_i8 v[34:37], v[188:191], v[204:207], v[34:37]
	v_mfma_i32_16x16x64_i8 v[22:25], v[180:183], v[212:215], v[22:25]
	v_mfma_i32_16x16x64_i8 v[18:21], v[188:191], v[212:215], v[18:21]
	v_mfma_i32_16x16x64_i8 v[6:9], v[180:183], v[220:223], v[6:9]
	v_mfma_i32_16x16x64_i8 v[2:5], v[188:191], v[220:223], v[2:5]
	v_mfma_i32_16x16x64_i8 v[54:57], v[184:187], v[200:203], v[54:57]
	v_mfma_i32_16x16x64_i8 v[50:53], v[192:195], v[200:203], v[50:53]
	v_mfma_i32_16x16x64_i8 v[38:41], v[184:187], v[208:211], v[38:41]
	v_mfma_i32_16x16x64_i8 v[34:37], v[192:195], v[208:211], v[34:37]
	v_mfma_i32_16x16x64_i8 v[22:25], v[184:187], v[216:219], v[22:25]
	v_mfma_i32_16x16x64_i8 v[18:21], v[192:195], v[216:219], v[18:21]
	v_mfma_i32_16x16x64_i8 v[6:9], v[184:187], v[224:227], v[6:9]
	v_mfma_i32_16x16x64_i8 v[2:5], v[192:195], v[224:227], v[2:5]
	s_barrier
; #define PG8_STAGE(bufoff, gbase, voff) do { _Pragma("unroll") for (int _i = 0; _i < 2; ++_i) \
;         __builtin_amdgcn_global_load_lds((const unsigned*)((const char*)(gbase) + (voff)[_i]), (LAS unsigned*)(lds + (bufoff) + ldsw + _i * 8192), 16, 0, 0); } while (0)
; #define PG8_LDA(dst, b, h) do { _Pragma("unroll") for (int m = 0; m < 4; ++m) _Pragma("unroll") for (int k = 0; k < 2; ++k) dst[m][k] = *(const LAS bf16x8*)(lds + PG8_SA(b, h) + aoff + m * 2048 + k * 1024); } while (0)
; #define PG8_LDB(dst, b, h) do { _Pragma("unroll") for (int n = 0; n < 2; ++n) _Pragma("unroll") for (int k = 0; k < 2; ++k) dst[n][k] = *(const LAS bf16x8*)(lds + PG8_SB(b, h) + boff + n * 2048 + k * 1024); } while (0)
; #define PG8_WAIT_V(n) asm volatile("s_waitcnt vmcnt(" #n ")" ::: "memory")
; #define PG8_WAIT_L(n) asm volatile("s_waitcnt lgkmcnt(" #n ")" ::: "memory")
; #define PG8_BAR __builtin_amdgcn_s_barrier()
; #define PG8_SCHED __builtin_amdgcn_sched_barrier(0)
; template <class Epi, class Sched, bool I8 = false>
; __device__ __forceinline__ void gemm_phase(LAS unsigned char* lds, const Gemm g, const Sched& S, const Epi& E) {
;     ...
;             PG8_LDB(B0, 1, 0); PG8_LDB(B1, 1, 1); PG8_SCHED; PG8_LDA(At, 1, 0); PG8_STAGE(PG8_SA(0, 1), a2 + hstepA, voffA);
;             PG8_WAIT_V(8); PG8_WAIT_L(0); PG8_BAR; PG8_MMA(0, 0, At, B0); PG8_MMA(0, 1, At, B1); PG8_BAR; PG8_SCHED;
;             PG8_LDA(At, 1, 1); PG8_STAGE(PG8_SB(1, 0), b3, voffB); PG8_STAGE(PG8_SB(1, 1), b3 + hstepB, voffB); PG8_STAGE(PG8_SA(1, 0), a3, voffA);
;             PG8_WAIT_V(8); PG8_WAIT_L(0); PG8_BAR; PG8_MMA(1, 0, At, B0); PG8_MMA(1, 1, At, B1); PG8_BAR; PG8_SCHED;
	s_add_i32 s54, 0, 0x18000
	v_add_u32_e32 v146, s54, v165
	s_add_i32 s55, 0, 0x1c000
	ds_read_b128 v[90:93], v146
	ds_read_b128 v[98:101], v146 offset:1024
	ds_read_b128 v[172:175], v146 offset:2048
	ds_read_b128 v[176:179], v146 offset:3072
	v_add_u32_e32 v146, s55, v165
	ds_read_b128 v[180:183], v146
	ds_read_b128 v[184:187], v146 offset:1024
	ds_read_b128 v[188:191], v146 offset:2048
	ds_read_b128 v[192:195], v146 offset:3072
	s_mov_b32 m0, s36
	s_nop 0
	global_load_lds_dwordx4 v144, s[26:27]
	s_mov_b32 m0, s37
	s_nop 0
	global_load_lds_dwordx4 v140, s[26:27]
	s_add_u32 s26, s26, 0x4000
	s_addc_u32 s27, s27, 0
	s_mov_b32 m0, s38
	ds_read_b128 v[196:199], v171 offset:32768
	ds_read_b128 v[200:203], v171 offset:33792
	ds_read_b128 v[204:207], v171 offset:34816
	ds_read_b128 v[208:211], v171 offset:35840
	ds_read_b128 v[212:215], v171 offset:36864
	ds_read_b128 v[216:219], v171 offset:37888
	ds_read_b128 v[220:223], v171 offset:38912
	ds_read_b128 v[224:227], v171 offset:39936
	global_load_lds_dwordx4 v144, s[26:27]
	s_mov_b32 m0, s39
	s_nop 0
	global_load_lds_dwordx4 v140, s[26:27]
	s_waitcnt vmcnt(8)
	s_waitcnt lgkmcnt(0)
	s_barrier
	v_mfma_i32_16x16x64_i8 v[134:137], v[90:93], v[196:199], v[134:137]
	v_mfma_i32_16x16x64_i8 v[130:133], v[172:175], v[196:199], v[130:133]
	v_mfma_i32_16x16x64_i8 v[118:121], v[90:93], v[204:207], v[118:121]
	v_mfma_i32_16x16x64_i8 v[114:117], v[172:175], v[204:207], v[114:117]
	v_mfma_i32_16x16x64_i8 v[102:105], v[90:93], v[212:215], v[102:105]
	v_mfma_i32_16x16x64_i8 v[94:97], v[172:175], v[212:215], v[94:97]
	v_mfma_i32_16x16x64_i8 v[78:81], v[90:93], v[220:223], v[78:81]
	v_mfma_i32_16x16x64_i8 v[74:77], v[172:175], v[220:223], v[74:77]
	v_mfma_i32_16x16x64_i8 v[134:137], v[98:101], v[200:203], v[134:137]
	v_mfma_i32_16x16x64_i8 v[130:133], v[176:179], v[200:203], v[130:133]
	v_mfma_i32_16x16x64_i8 v[118:121], v[98:101], v[208:211], v[118:121]
	v_mfma_i32_16x16x64_i8 v[114:117], v[176:179], v[208:211], v[114:117]
	v_mfma_i32_16x16x64_i8 v[102:105], v[98:101], v[216:219], v[102:105]
	v_mfma_i32_16x16x64_i8 v[94:97], v[176:179], v[216:219], v[94:97]
	v_mfma_i32_16x16x64_i8 v[78:81], v[98:101], v[224:227], v[78:81]
	v_mfma_i32_16x16x64_i8 v[74:77], v[176:179], v[224:227], v[74:77]
	v_mfma_i32_16x16x64_i8 v[126:129], v[180:183], v[196:199], v[126:129]
	v_mfma_i32_16x16x64_i8 v[122:125], v[188:191], v[196:199], v[122:125]
	v_mfma_i32_16x16x64_i8 v[110:113], v[180:183], v[204:207], v[110:113]
	v_mfma_i32_16x16x64_i8 v[106:109], v[188:191], v[204:207], v[106:109]
	v_mfma_i32_16x16x64_i8 v[86:89], v[180:183], v[212:215], v[86:89]
	v_mfma_i32_16x16x64_i8 v[82:85], v[188:191], v[212:215], v[82:85]
	v_mfma_i32_16x16x64_i8 v[70:73], v[180:183], v[220:223], v[70:73]
	v_mfma_i32_16x16x64_i8 v[66:69], v[188:191], v[220:223], v[66:69]
	v_mfma_i32_16x16x64_i8 v[126:129], v[184:187], v[200:203], v[126:129]
	v_mfma_i32_16x16x64_i8 v[122:125], v[192:195], v[200:203], v[122:125]
	v_mfma_i32_16x16x64_i8 v[110:113], v[184:187], v[208:211], v[110:113]
	v_mfma_i32_16x16x64_i8 v[106:109], v[192:195], v[208:211], v[106:109]
	v_mfma_i32_16x16x64_i8 v[86:89], v[184:187], v[216:219], v[86:89]
	v_mfma_i32_16x16x64_i8 v[82:85], v[192:195], v[216:219], v[82:85]
	v_mfma_i32_16x16x64_i8 v[70:73], v[184:187], v[224:227], v[70:73]
	v_mfma_i32_16x16x64_i8 v[66:69], v[192:195], v[224:227], v[66:69]
	s_barrier
	s_add_u32 s26, s24, 0x8000
	s_addc_u32 s27, s25, 0
	s_add_i32 s54, s54, s33
	s_mov_b32 m0, s54
	ds_read_b128 v[196:199], v171 offset:49152
	ds_read_b128 v[200:203], v171 offset:50176
	ds_read_b128 v[204:207], v171 offset:51200
	ds_read_b128 v[208:211], v171 offset:52224
	ds_read_b128 v[212:215], v171 offset:53248
	ds_read_b128 v[216:219], v171 offset:54272
	ds_read_b128 v[220:223], v171 offset:55296
	ds_read_b128 v[224:227], v171 offset:56320
	global_load_lds_dwordx4 v142, s[26:27]
	s_add_i32 m0, s54, 0x2000
	s_add_u32 s24, s24, 0xc000
	v_lshl_add_u64 v[158:159], s[26:27], 0, v[138:139]
	s_addc_u32 s25, s25, 0
	s_add_i32 s26, s55, s33
	global_load_lds_dwordx4 v[158:159], off
	s_mov_b32 m0, s26
	s_nop 0
	global_load_lds_dwordx4 v142, s[24:25]
	s_add_i32 m0, s26, 0x2000
	s_nop 0
	global_load_lds_dwordx4 v138, s[24:25]
	s_waitcnt vmcnt(6)
	s_waitcnt lgkmcnt(0)
	s_barrier
	v_mfma_i32_16x16x64_i8 v[62:65], v[90:93], v[196:199], v[62:65]
	v_mfma_i32_16x16x64_i8 v[58:61], v[172:175], v[196:199], v[58:61]
	v_mfma_i32_16x16x64_i8 v[46:49], v[90:93], v[204:207], v[46:49]
	v_mfma_i32_16x16x64_i8 v[42:45], v[172:175], v[204:207], v[42:45]
	v_mfma_i32_16x16x64_i8 v[30:33], v[90:93], v[212:215], v[30:33]
	v_mfma_i32_16x16x64_i8 v[26:29], v[172:175], v[212:215], v[26:29]
	v_mfma_i32_16x16x64_i8 v[14:17], v[90:93], v[220:223], v[14:17]
	v_mfma_i32_16x16x64_i8 v[10:13], v[172:175], v[220:223], v[10:13]
	v_mfma_i32_16x16x64_i8 v[62:65], v[98:101], v[200:203], v[62:65]
	v_mfma_i32_16x16x64_i8 v[58:61], v[176:179], v[200:203], v[58:61]
	v_mfma_i32_16x16x64_i8 v[46:49], v[98:101], v[208:211], v[46:49]
	v_mfma_i32_16x16x64_i8 v[42:45], v[176:179], v[208:211], v[42:45]
	v_mfma_i32_16x16x64_i8 v[30:33], v[98:101], v[216:219], v[30:33]
	v_mfma_i32_16x16x64_i8 v[26:29], v[176:179], v[216:219], v[26:29]
	v_mfma_i32_16x16x64_i8 v[14:17], v[98:101], v[224:227], v[14:17]
	v_mfma_i32_16x16x64_i8 v[10:13], v[176:179], v[224:227], v[10:13]
	v_mfma_i32_16x16x64_i8 v[54:57], v[180:183], v[196:199], v[54:57]
	v_mfma_i32_16x16x64_i8 v[50:53], v[188:191], v[196:199], v[50:53]
	v_mfma_i32_16x16x64_i8 v[38:41], v[180:183], v[204:207], v[38:41]
	v_mfma_i32_16x16x64_i8 v[34:37], v[188:191], v[204:207], v[34:37]
	v_mfma_i32_16x16x64_i8 v[22:25], v[180:183], v[212:215], v[22:25]
	v_mfma_i32_16x16x64_i8 v[18:21], v[188:191], v[212:215], v[18:21]
	v_mfma_i32_16x16x64_i8 v[6:9], v[180:183], v[220:223], v[6:9]
	v_mfma_i32_16x16x64_i8 v[2:5], v[188:191], v[220:223], v[2:5]
	v_mfma_i32_16x16x64_i8 v[54:57], v[184:187], v[200:203], v[54:57]
	v_mfma_i32_16x16x64_i8 v[50:53], v[192:195], v[200:203], v[50:53]
	v_mfma_i32_16x16x64_i8 v[38:41], v[184:187], v[208:211], v[38:41]
	v_mfma_i32_16x16x64_i8 v[34:37], v[192:195], v[208:211], v[34:37]
	v_mfma_i32_16x16x64_i8 v[22:25], v[184:187], v[216:219], v[22:25]
	v_mfma_i32_16x16x64_i8 v[18:21], v[192:195], v[216:219], v[18:21]
	v_mfma_i32_16x16x64_i8 v[6:9], v[184:187], v[224:227], v[6:9]
	v_mfma_i32_16x16x64_i8 v[2:5], v[192:195], v[224:227], v[2:5]
	s_barrier
	s_add_i32 s53, s53, 2
	s_add_u32 s20, s20, 0x10000
	s_addc_u32 s21, s21, 0
	s_add_u32 s51, s51, 0x10000
	s_addc_u32 s52, s52, 0
	s_cmp_gt_u32 s53, 29
	s_cbranch_scc0 .LBB0_1169
	s_and_b64 vcc, exec, s[8:9]
	s_cbranch_vccz .LBB0_1172
	s_barrier

; #define PG8_STAGE(bufoff, gbase, voff) do { _Pragma("unroll") for (int _i = 0; _i < 2; ++_i) \
;         __builtin_amdgcn_global_load_lds((const unsigned*)((const char*)(gbase) + (voff)[_i]), (LAS unsigned*)(lds + (bufoff) + ldsw + _i * 8192), 16, 0, 0); } while (0)
; #define PG8_LDA(dst, b, h) do { _Pragma("unroll") for (int m = 0; m < 4; ++m) _Pragma("unroll") for (int k = 0; k < 2; ++k) dst[m][k] = *(const LAS bf16x8*)(lds + PG8_SA(b, h) + aoff + m * 2048 + k * 1024); } while (0)
; #define PG8_LDB(dst, b, h) do { _Pragma("unroll") for (int n = 0; n < 2; ++n) _Pragma("unroll") for (int k = 0; k < 2; ++k) dst[n][k] = *(const LAS bf16x8*)(lds + PG8_SB(b, h) + boff + n * 2048 + k * 1024); } while (0)
; #define PG8_WAIT_V(n) asm volatile("s_waitcnt vmcnt(" #n ")" ::: "memory")
; #define PG8_WAIT_L(n) asm volatile("s_waitcnt lgkmcnt(" #n ")" ::: "memory")
; #define PG8_BAR __builtin_amdgcn_s_barrier()
; #define PG8_SCHED __builtin_amdgcn_sched_barrier(0)
; template <class Epi, class Sched, bool I8 = false>
; __device__ __forceinline__ void gemm_phase(LAS unsigned char* lds, const Gemm g, const Sched& S, const Epi& E) {
;     ...
;             const bool last = (t == nt - 2);
;             const char* a1 = cA + (size_t)(t + 1) * kstep;
;             const char* a2 = last ? nA : cA + (size_t)(t + 2) * kstep; const char* b2 = last ? nB : cB + (size_t)(t + 2) * kstep;
;             const char* a3 = a2 + kstep; const char* b3 = b2 + kstep;
;             PG8_LDB(B0, 0, 0); PG8_LDB(B1, 0, 1); PG8_SCHED; PG8_LDA(At, 0, 0); PG8_STAGE(PG8_SA(1, 1), a1 + hstepA, voffA);
;             PG8_WAIT_V(8); PG8_WAIT_L(0); PG8_BAR; PG8_MMA(0, 0, At, B0); PG8_MMA(0, 1, At, B1); PG8_BAR; PG8_SCHED;
;             PG8_LDA(At, 0, 1); PG8_STAGE(PG8_SB(0, 0), b2, voffB); PG8_STAGE(PG8_SB(0, 1), b2 + hstepB, voffB); PG8_STAGE(PG8_SA(0, 0), a2, voffA);
;             PG8_WAIT_V(8); PG8_WAIT_L(0); PG8_BAR; PG8_MMA(1, 0, At, B0); PG8_MMA(1, 1, At, B1); PG8_BAR; PG8_SCHED;
.LBB0_1393:
	ds_read_b128 v[66:69], v180
	ds_read_b128 v[70:73], v180 offset:1024
	ds_read_b128 v[74:77], v180 offset:2048
	ds_read_b128 v[78:81], v180 offset:3072
	ds_read_b128 v[146:149], v181
	ds_read_b128 v[150:153], v181 offset:1024
	ds_read_b128 v[174:177], v181 offset:2048
	ds_read_b128 v[184:187], v181 offset:3072
	s_add_u32 s20, s18, 0x4000
	s_addc_u32 s21, s19, 0
	s_cmpk_eq_i32 s49, 0x52
	s_cselect_b32 s24, s0, s20
	s_cselect_b32 s25, s1, s21
	s_cselect_b32 s22, s16, s47
	s_cselect_b32 s23, s17, s48
	s_add_u32 s20, s24, 0x8000
	s_addc_u32 s21, s25, 0
	s_sub_u32 s98, s18, 0x4000
	s_subb_u32 s99, s19, 0
	s_mov_b32 m0, s37
	s_nop 0
	global_load_lds_dwordx4 v156, s[98:99]
	s_mov_b32 m0, s38
	s_nop 0
	global_load_lds_dwordx4 v160, s[98:99]
	s_add_i32 m0, s31, 0xc000
	ds_read_b128 v[188:191], v182
	ds_read_b128 v[192:195], v182 offset:1024
	ds_read_b128 v[196:199], v182 offset:2048
	ds_read_b128 v[200:203], v182 offset:3072
	ds_read_b128 v[204:207], v182 offset:4096
	ds_read_b128 v[208:211], v182 offset:5120
	ds_read_b128 v[212:215], v182 offset:6144
	ds_read_b128 v[216:219], v182 offset:7168
	global_load_lds_dwordx4 v166, s[18:19]
	s_add_i32 m0, s31, 0xe000
	s_nop 0
	global_load_lds_dwordx4 v168, s[18:19]
	s_waitcnt vmcnt(8)
	s_waitcnt lgkmcnt(0)
	s_barrier
	v_mfma_i32_16x16x64_i8 v[142:145], v[66:69], v[188:191], v[142:145]
	v_mfma_i32_16x16x64_i8 v[138:141], v[74:77], v[188:191], v[138:141]
	v_mfma_i32_16x16x64_i8 v[126:129], v[66:69], v[196:199], v[126:129]
	v_mfma_i32_16x16x64_i8 v[122:125], v[74:77], v[196:199], v[122:125]
	v_mfma_i32_16x16x64_i8 v[110:113], v[66:69], v[204:207], v[110:113]
	v_mfma_i32_16x16x64_i8 v[106:109], v[74:77], v[204:207], v[106:109]
	v_mfma_i32_16x16x64_i8 v[94:97], v[66:69], v[212:215], v[94:97]
	v_mfma_i32_16x16x64_i8 v[90:93], v[74:77], v[212:215], v[90:93]
	v_mfma_i32_16x16x64_i8 v[142:145], v[70:73], v[192:195], v[142:145]
	v_mfma_i32_16x16x64_i8 v[138:141], v[78:81], v[192:195], v[138:141]
	v_mfma_i32_16x16x64_i8 v[126:129], v[70:73], v[200:203], v[126:129]
	v_mfma_i32_16x16x64_i8 v[122:125], v[78:81], v[200:203], v[122:125]
	v_mfma_i32_16x16x64_i8 v[110:113], v[70:73], v[208:211], v[110:113]
	v_mfma_i32_16x16x64_i8 v[106:109], v[78:81], v[208:211], v[106:109]
	v_mfma_i32_16x16x64_i8 v[94:97], v[70:73], v[216:219], v[94:97]
	v_mfma_i32_16x16x64_i8 v[90:93], v[78:81], v[216:219], v[90:93]
	v_mfma_i32_16x16x64_i8 v[134:137], v[146:149], v[188:191], v[134:137]
	v_mfma_i32_16x16x64_i8 v[130:133], v[174:177], v[188:191], v[130:133]
	v_mfma_i32_16x16x64_i8 v[118:121], v[146:149], v[196:199], v[118:121]
	v_mfma_i32_16x16x64_i8 v[114:117], v[174:177], v[196:199], v[114:117]
	v_mfma_i32_16x16x64_i8 v[102:105], v[146:149], v[204:207], v[102:105]
	v_mfma_i32_16x16x64_i8 v[98:101], v[174:177], v[204:207], v[98:101]
	v_mfma_i32_16x16x64_i8 v[86:89], v[146:149], v[212:215], v[86:89]
	v_mfma_i32_16x16x64_i8 v[82:85], v[174:177], v[212:215], v[82:85]
	v_mfma_i32_16x16x64_i8 v[134:137], v[150:153], v[192:195], v[134:137]
	v_mfma_i32_16x16x64_i8 v[130:133], v[184:187], v[192:195], v[130:133]
	v_mfma_i32_16x16x64_i8 v[118:121], v[150:153], v[200:203], v[118:121]
	v_mfma_i32_16x16x64_i8 v[114:117], v[184:187], v[200:203], v[114:117]
	v_mfma_i32_16x16x64_i8 v[102:105], v[150:153], v[208:211], v[102:105]
	v_mfma_i32_16x16x64_i8 v[98:101], v[184:187], v[208:211], v[98:101]
	v_mfma_i32_16x16x64_i8 v[86:89], v[150:153], v[216:219], v[86:89]
	v_mfma_i32_16x16x64_i8 v[82:85], v[184:187], v[216:219], v[82:85]
	s_barrier
	s_add_i32 s50, s41, s30
	s_mov_b32 m0, s50
	ds_read_b128 v[188:191], v182 offset:16384
	ds_read_b128 v[192:195], v182 offset:17408
	ds_read_b128 v[196:199], v182 offset:18432
	ds_read_b128 v[200:203], v182 offset:19456
	ds_read_b128 v[204:207], v182 offset:20480
	ds_read_b128 v[208:211], v182 offset:21504
	ds_read_b128 v[212:215], v182 offset:22528
	ds_read_b128 v[216:219], v182 offset:23552
	global_load_lds_dwordx4 v158, s[22:23]
	s_add_i32 m0, s50, 0x2000
	s_add_u32 s50, s22, 0x4000
	s_addc_u32 s51, s23, 0
	s_add_i32 s52, s42, s30
	global_load_lds_dwordx4 v162, s[22:23]
	s_mov_b32 m0, s52
	s_nop 0
	global_load_lds_dwordx4 v158, s[50:51]
	s_add_i32 m0, s52, 0x2000
	s_nop 0
	global_load_lds_dwordx4 v162, s[50:51]
	s_waitcnt vmcnt(6)
	s_waitcnt lgkmcnt(0)
	s_barrier
	v_mfma_i32_16x16x64_i8 v[62:65], v[66:69], v[188:191], v[62:65]
	v_mfma_i32_16x16x64_i8 v[58:61], v[74:77], v[188:191], v[58:61]
	v_mfma_i32_16x16x64_i8 v[46:49], v[66:69], v[196:199], v[46:49]
	v_mfma_i32_16x16x64_i8 v[42:45], v[74:77], v[196:199], v[42:45]
	v_mfma_i32_16x16x64_i8 v[30:33], v[66:69], v[204:207], v[30:33]
	v_mfma_i32_16x16x64_i8 v[26:29], v[74:77], v[204:207], v[26:29]
	v_mfma_i32_16x16x64_i8 v[14:17], v[66:69], v[212:215], v[14:17]
	v_mfma_i32_16x16x64_i8 v[10:13], v[74:77], v[212:215], v[10:13]
	v_mfma_i32_16x16x64_i8 v[62:65], v[70:73], v[192:195], v[62:65]
	v_mfma_i32_16x16x64_i8 v[58:61], v[78:81], v[192:195], v[58:61]
	v_mfma_i32_16x16x64_i8 v[46:49], v[70:73], v[200:203], v[46:49]
	v_mfma_i32_16x16x64_i8 v[42:45], v[78:81], v[200:203], v[42:45]
	v_mfma_i32_16x16x64_i8 v[30:33], v[70:73], v[208:211], v[30:33]
	v_mfma_i32_16x16x64_i8 v[26:29], v[78:81], v[208:211], v[26:29]
	v_mfma_i32_16x16x64_i8 v[14:17], v[70:73], v[216:219], v[14:17]
	v_mfma_i32_16x16x64_i8 v[10:13], v[78:81], v[216:219], v[10:13]
	v_mfma_i32_16x16x64_i8 v[54:57], v[146:149], v[188:191], v[54:57]
	v_mfma_i32_16x16x64_i8 v[50:53], v[174:177], v[188:191], v[50:53]
	v_mfma_i32_16x16x64_i8 v[38:41], v[146:149], v[196:199], v[38:41]
	v_mfma_i32_16x16x64_i8 v[34:37], v[174:177], v[196:199], v[34:37]
	v_mfma_i32_16x16x64_i8 v[22:25], v[146:149], v[204:207], v[22:25]
	v_mfma_i32_16x16x64_i8 v[18:21], v[174:177], v[204:207], v[18:21]
	v_mfma_i32_16x16x64_i8 v[6:9], v[146:149], v[212:215], v[6:9]
	v_mfma_i32_16x16x64_i8 v[2:5], v[174:177], v[212:215], v[2:5]
	v_mfma_i32_16x16x64_i8 v[54:57], v[150:153], v[192:195], v[54:57]
	v_mfma_i32_16x16x64_i8 v[50:53], v[184:187], v[192:195], v[50:53]
	v_mfma_i32_16x16x64_i8 v[38:41], v[150:153], v[200:203], v[38:41]
	v_mfma_i32_16x16x64_i8 v[34:37], v[184:187], v[200:203], v[34:37]
	v_mfma_i32_16x16x64_i8 v[22:25], v[150:153], v[208:211], v[22:25]
	v_mfma_i32_16x16x64_i8 v[18:21], v[184:187], v[208:211], v[18:21]
	v_mfma_i32_16x16x64_i8 v[6:9], v[150:153], v[216:219], v[6:9]
	v_mfma_i32_16x16x64_i8 v[2:5], v[184:187], v[216:219], v[2:5]
	s_barrier
; #define PG8_STAGE(bufoff, gbase, voff) do { _Pragma("unroll") for (int _i = 0; _i < 2; ++_i) \
;         __builtin_amdgcn_global_load_lds((const unsigned*)((const char*)(gbase) + (voff)[_i]), (LAS unsigned*)(lds + (bufoff) + ldsw + _i * 8192), 16, 0, 0); } while (0)
; #define PG8_LDA(dst, b, h) do { _Pragma("unroll") for (int m = 0; m < 4; ++m) _Pragma("unroll") for (int k = 0; k < 2; ++k) dst[m][k] = *(const LAS bf16x8*)(lds + PG8_SA(b, h) + aoff + m * 2048 + k * 1024); } while (0)
; #define PG8_LDB(dst, b, h) do { _Pragma("unroll") for (int n = 0; n < 2; ++n) _Pragma("unroll") for (int k = 0; k < 2; ++k) dst[n][k] = *(const LAS bf16x8*)(lds + PG8_SB(b, h) + boff + n * 2048 + k * 1024); } while (0)
; #define PG8_WAIT_V(n) asm volatile("s_waitcnt vmcnt(" #n ")" ::: "memory")
; #define PG8_WAIT_L(n) asm volatile("s_waitcnt lgkmcnt(" #n ")" ::: "memory")
; #define PG8_BAR __builtin_amdgcn_s_barrier()
; #define PG8_SCHED __builtin_amdgcn_sched_barrier(0)
; template <class Epi, class Sched, bool I8 = false>
; __device__ __forceinline__ void gemm_phase(LAS unsigned char* lds, const Gemm g, const Sched& S, const Epi& E) {
;     ...
;             PG8_LDB(B0, 1, 0); PG8_LDB(B1, 1, 1); PG8_SCHED; PG8_LDA(At, 1, 0); PG8_STAGE(PG8_SA(0, 1), a2 + hstepA, voffA);
;             PG8_WAIT_V(8); PG8_WAIT_L(0); PG8_BAR; PG8_MMA(0, 0, At, B0); PG8_MMA(0, 1, At, B1); PG8_BAR; PG8_SCHED;
;             PG8_LDA(At, 1, 1); PG8_STAGE(PG8_SB(1, 0), b3, voffB); PG8_STAGE(PG8_SB(1, 1), b3 + hstepB, voffB); PG8_STAGE(PG8_SA(1, 0), a3, voffA);
;             PG8_WAIT_V(8); PG8_WAIT_L(0); PG8_BAR; PG8_MMA(1, 0, At, B0); PG8_MMA(1, 1, At, B1); PG8_BAR; PG8_SCHED;
;         }
	s_add_i32 s50, 0, 0x18000
	s_add_i32 s51, 0, 0x1c000
	v_add_u32_e32 v78, s50, v178
	v_add_u32_e32 v164, s51, v178
	ds_read_b128 v[66:69], v78
	ds_read_b128 v[70:73], v78 offset:1024
	ds_read_b128 v[74:77], v78 offset:2048
	ds_read_b128 v[78:81], v78 offset:3072
	ds_read_b128 v[146:149], v164
	ds_read_b128 v[150:153], v164 offset:1024
	ds_read_b128 v[174:177], v164 offset:2048
	ds_read_b128 v[184:187], v164 offset:3072
	s_mov_b32 m0, s31
	s_nop 0
	global_load_lds_dwordx4 v156, s[24:25]
	s_mov_b32 m0, s33
	s_nop 0
	global_load_lds_dwordx4 v160, s[24:25]
	s_add_u32 s24, s24, 0x4000
	s_addc_u32 s25, s25, 0
	s_mov_b32 m0, s34
	ds_read_b128 v[188:191], v182 offset:32768
	ds_read_b128 v[192:195], v182 offset:33792
	ds_read_b128 v[196:199], v182 offset:34816
	ds_read_b128 v[200:203], v182 offset:35840
	ds_read_b128 v[204:207], v182 offset:36864
	ds_read_b128 v[208:211], v182 offset:37888
	ds_read_b128 v[212:215], v182 offset:38912
	ds_read_b128 v[216:219], v182 offset:39936
	global_load_lds_dwordx4 v156, s[24:25]
	s_mov_b32 m0, s35
	s_nop 0
	global_load_lds_dwordx4 v160, s[24:25]
	s_waitcnt vmcnt(8)
	s_waitcnt lgkmcnt(0)
	s_barrier
	v_mfma_i32_16x16x64_i8 v[142:145], v[66:69], v[188:191], v[142:145]
	v_mfma_i32_16x16x64_i8 v[138:141], v[74:77], v[188:191], v[138:141]
	v_mfma_i32_16x16x64_i8 v[126:129], v[66:69], v[196:199], v[126:129]
	v_mfma_i32_16x16x64_i8 v[122:125], v[74:77], v[196:199], v[122:125]
	v_mfma_i32_16x16x64_i8 v[110:113], v[66:69], v[204:207], v[110:113]
	v_mfma_i32_16x16x64_i8 v[106:109], v[74:77], v[204:207], v[106:109]
	v_mfma_i32_16x16x64_i8 v[94:97], v[66:69], v[212:215], v[94:97]
	v_mfma_i32_16x16x64_i8 v[90:93], v[74:77], v[212:215], v[90:93]
	v_mfma_i32_16x16x64_i8 v[142:145], v[70:73], v[192:195], v[142:145]
	v_mfma_i32_16x16x64_i8 v[138:141], v[78:81], v[192:195], v[138:141]
	v_mfma_i32_16x16x64_i8 v[126:129], v[70:73], v[200:203], v[126:129]
	v_mfma_i32_16x16x64_i8 v[122:125], v[78:81], v[200:203], v[122:125]
	v_mfma_i32_16x16x64_i8 v[110:113], v[70:73], v[208:211], v[110:113]
	v_mfma_i32_16x16x64_i8 v[106:109], v[78:81], v[208:211], v[106:109]
	v_mfma_i32_16x16x64_i8 v[94:97], v[70:73], v[216:219], v[94:97]
	v_mfma_i32_16x16x64_i8 v[90:93], v[78:81], v[216:219], v[90:93]
	v_mfma_i32_16x16x64_i8 v[134:137], v[146:149], v[188:191], v[134:137]
	v_mfma_i32_16x16x64_i8 v[130:133], v[174:177], v[188:191], v[130:133]
	v_mfma_i32_16x16x64_i8 v[118:121], v[146:149], v[196:199], v[118:121]
	v_mfma_i32_16x16x64_i8 v[114:117], v[174:177], v[196:199], v[114:117]
	v_mfma_i32_16x16x64_i8 v[102:105], v[146:149], v[204:207], v[102:105]
	v_mfma_i32_16x16x64_i8 v[98:101], v[174:177], v[204:207], v[98:101]
	v_mfma_i32_16x16x64_i8 v[86:89], v[146:149], v[212:215], v[86:89]
	v_mfma_i32_16x16x64_i8 v[82:85], v[174:177], v[212:215], v[82:85]
	v_mfma_i32_16x16x64_i8 v[134:137], v[150:153], v[192:195], v[134:137]
	v_mfma_i32_16x16x64_i8 v[130:133], v[184:187], v[192:195], v[130:133]
	v_mfma_i32_16x16x64_i8 v[118:121], v[150:153], v[200:203], v[118:121]
	v_mfma_i32_16x16x64_i8 v[114:117], v[184:187], v[200:203], v[114:117]
	v_mfma_i32_16x16x64_i8 v[102:105], v[150:153], v[208:211], v[102:105]
	v_mfma_i32_16x16x64_i8 v[98:101], v[184:187], v[208:211], v[98:101]
	v_mfma_i32_16x16x64_i8 v[86:89], v[150:153], v[216:219], v[86:89]
	v_mfma_i32_16x16x64_i8 v[82:85], v[184:187], v[216:219], v[82:85]
	s_barrier
	s_add_u32 s24, s22, 0x8000
	s_addc_u32 s25, s23, 0
	s_add_i32 s50, s50, s30
	s_mov_b32 m0, s50
	ds_read_b128 v[188:191], v182 offset:49152
	ds_read_b128 v[192:195], v182 offset:50176
	ds_read_b128 v[196:199], v182 offset:51200
	ds_read_b128 v[200:203], v182 offset:52224
	ds_read_b128 v[204:207], v182 offset:53248
	ds_read_b128 v[208:211], v182 offset:54272
	ds_read_b128 v[212:215], v182 offset:55296
	ds_read_b128 v[216:219], v182 offset:56320
	global_load_lds_dwordx4 v158, s[24:25]
	s_add_i32 m0, s50, 0x2000
	s_add_u32 s22, s22, 0xc000
	v_lshl_add_u64 v[220:221], s[24:25], 0, v[162:163]
	s_addc_u32 s23, s23, 0
	s_add_i32 s24, s51, s30
	global_load_lds_dwordx4 v[220:221], off
	s_mov_b32 m0, s24
	s_nop 0
	global_load_lds_dwordx4 v158, s[22:23]
	s_add_i32 m0, s24, 0x2000
	s_nop 0
	global_load_lds_dwordx4 v162, s[22:23]
	s_waitcnt vmcnt(6)
	s_waitcnt lgkmcnt(0)
	s_barrier
	v_mfma_i32_16x16x64_i8 v[62:65], v[66:69], v[188:191], v[62:65]
	v_mfma_i32_16x16x64_i8 v[58:61], v[74:77], v[188:191], v[58:61]
	v_mfma_i32_16x16x64_i8 v[46:49], v[66:69], v[196:199], v[46:49]
	v_mfma_i32_16x16x64_i8 v[42:45], v[74:77], v[196:199], v[42:45]
	v_mfma_i32_16x16x64_i8 v[30:33], v[66:69], v[204:207], v[30:33]
	v_mfma_i32_16x16x64_i8 v[26:29], v[74:77], v[204:207], v[26:29]
	v_mfma_i32_16x16x64_i8 v[14:17], v[66:69], v[212:215], v[14:17]
	v_mfma_i32_16x16x64_i8 v[10:13], v[74:77], v[212:215], v[10:13]
	v_mfma_i32_16x16x64_i8 v[62:65], v[70:73], v[192:195], v[62:65]
	v_mfma_i32_16x16x64_i8 v[58:61], v[78:81], v[192:195], v[58:61]
	v_mfma_i32_16x16x64_i8 v[46:49], v[70:73], v[200:203], v[46:49]
	v_mfma_i32_16x16x64_i8 v[42:45], v[78:81], v[200:203], v[42:45]
	v_mfma_i32_16x16x64_i8 v[30:33], v[70:73], v[208:211], v[30:33]
	v_mfma_i32_16x16x64_i8 v[26:29], v[78:81], v[208:211], v[26:29]
	v_mfma_i32_16x16x64_i8 v[14:17], v[70:73], v[216:219], v[14:17]
	v_mfma_i32_16x16x64_i8 v[10:13], v[78:81], v[216:219], v[10:13]
	v_mfma_i32_16x16x64_i8 v[54:57], v[146:149], v[188:191], v[54:57]
	v_mfma_i32_16x16x64_i8 v[50:53], v[174:177], v[188:191], v[50:53]
	v_mfma_i32_16x16x64_i8 v[38:41], v[146:149], v[196:199], v[38:41]
	v_mfma_i32_16x16x64_i8 v[34:37], v[174:177], v[196:199], v[34:37]
	v_mfma_i32_16x16x64_i8 v[22:25], v[146:149], v[204:207], v[22:25]
	v_mfma_i32_16x16x64_i8 v[18:21], v[174:177], v[204:207], v[18:21]
	v_mfma_i32_16x16x64_i8 v[6:9], v[146:149], v[212:215], v[6:9]
	v_mfma_i32_16x16x64_i8 v[2:5], v[174:177], v[212:215], v[2:5]
	v_mfma_i32_16x16x64_i8 v[54:57], v[150:153], v[192:195], v[54:57]
	v_mfma_i32_16x16x64_i8 v[50:53], v[184:187], v[192:195], v[50:53]
	v_mfma_i32_16x16x64_i8 v[38:41], v[150:153], v[200:203], v[38:41]
	v_mfma_i32_16x16x64_i8 v[34:37], v[184:187], v[200:203], v[34:37]
	v_mfma_i32_16x16x64_i8 v[22:25], v[150:153], v[208:211], v[22:25]
	v_mfma_i32_16x16x64_i8 v[18:21], v[184:187], v[208:211], v[18:21]
	v_mfma_i32_16x16x64_i8 v[6:9], v[150:153], v[216:219], v[6:9]
	v_mfma_i32_16x16x64_i8 v[2:5], v[184:187], v[216:219], v[2:5]
	s_barrier
	s_add_i32 s49, s49, 2
	s_add_u32 s18, s18, 0x10000
	s_addc_u32 s19, s19, 0
	s_add_u32 s47, s47, 0x10000
	s_addc_u32 s48, s48, 0
	s_cmpk_gt_u32 s49, 0x53
	s_cbranch_scc0 .LBB0_1393
	s_and_b64 vcc, exec, s[14:15]
	s_cbranch_vccz .LBB0_1396
	s_barrier

; #define PG8_STAGE(bufoff, gbase, voff) do { _Pragma("unroll") for (int _i = 0; _i < 2; ++_i) \
;         __builtin_amdgcn_global_load_lds((const unsigned*)((const char*)(gbase) + (voff)[_i]), (LAS unsigned*)(lds + (bufoff) + ldsw + _i * 8192), 16, 0, 0); } while (0)
; #define PG8_LDA(dst, b, h) do { _Pragma("unroll") for (int m = 0; m < 4; ++m) _Pragma("unroll") for (int k = 0; k < 2; ++k) dst[m][k] = *(const LAS bf16x8*)(lds + PG8_SA(b, h) + aoff + m * 2048 + k * 1024); } while (0)
; #define PG8_LDB(dst, b, h) do { _Pragma("unroll") for (int n = 0; n < 2; ++n) _Pragma("unroll") for (int k = 0; k < 2; ++k) dst[n][k] = *(const LAS bf16x8*)(lds + PG8_SB(b, h) + boff + n * 2048 + k * 1024); } while (0)
; #define PG8_WAIT_V(n) asm volatile("s_waitcnt vmcnt(" #n ")" ::: "memory")
; #define PG8_WAIT_L(n) asm volatile("s_waitcnt lgkmcnt(" #n ")" ::: "memory")
; #define PG8_BAR __builtin_amdgcn_s_barrier()
; #define PG8_SCHED __builtin_amdgcn_sched_barrier(0)
; template <class Epi, class Sched, bool I8 = false>
; __device__ __forceinline__ void gemm_phase(LAS unsigned char* lds, const Gemm g, const Sched& S, const Epi& E) {
;     ...
;             const bool last = (t == nt - 2);
;             const char* a1 = cA + (size_t)(t + 1) * kstep;
;             const char* a2 = last ? nA : cA + (size_t)(t + 2) * kstep; const char* b2 = last ? nB : cB + (size_t)(t + 2) * kstep;
;             const char* a3 = a2 + kstep; const char* b3 = b2 + kstep;
;             PG8_LDB(B0, 0, 0); PG8_LDB(B1, 0, 1); PG8_SCHED; PG8_LDA(At, 0, 0); PG8_STAGE(PG8_SA(1, 1), a1 + hstepA, voffA);
;             PG8_WAIT_V(8); PG8_WAIT_L(0); PG8_BAR; PG8_MMA(0, 0, At, B0); PG8_MMA(0, 1, At, B1); PG8_BAR; PG8_SCHED;
;             PG8_LDA(At, 0, 1); PG8_STAGE(PG8_SB(0, 0), b2, voffB); PG8_STAGE(PG8_SB(0, 1), b2 + hstepB, voffB); PG8_STAGE(PG8_SA(0, 0), a2, voffA);
;             PG8_WAIT_V(8); PG8_WAIT_L(0); PG8_BAR; PG8_MMA(1, 0, At, B0); PG8_MMA(1, 1, At, B1); PG8_BAR; PG8_SCHED;
.LBB0_1482:
	ds_read_b128 v[152:155], v182
	ds_read_b128 v[156:159], v182 offset:1024
	ds_read_b128 v[160:163], v182 offset:2048
	ds_read_b128 v[164:167], v182 offset:3072
	ds_read_b128 v[168:171], v183
	ds_read_b128 v[172:175], v183 offset:1024
	ds_read_b128 v[176:179], v183 offset:2048
	ds_read_b128 v[186:189], v183 offset:3072
	s_add_u32 s38, s8, 0x4000
	s_addc_u32 s39, s9, 0
	s_cmp_eq_u32 s47, 60
	s_cselect_b32 s42, s31, s38
	s_cselect_b32 s43, s7, s39
	s_cselect_b32 s40, s44, s45
	s_cselect_b32 s41, s29, s46
	s_add_u32 s38, s42, 0x8000
	s_addc_u32 s39, s43, 0
	s_sub_u32 s98, s8, 0x4000
	s_subb_u32 s99, s9, 0
	s_mov_b32 m0, s58
	s_nop 0
	global_load_lds_dwordx4 v130, s[98:99]
	s_mov_b32 m0, s59
	s_nop 0
	global_load_lds_dwordx4 v134, s[98:99]
	s_add_i32 m0, s33, 0xc000
	ds_read_b128 v[190:193], v184
	ds_read_b128 v[194:197], v184 offset:1024
	ds_read_b128 v[198:201], v184 offset:2048
	ds_read_b128 v[202:205], v184 offset:3072
	ds_read_b128 v[206:209], v184 offset:4096
	ds_read_b128 v[210:213], v184 offset:5120
	ds_read_b128 v[214:217], v184 offset:6144
	ds_read_b128 v[218:221], v184 offset:7168
	global_load_lds_dwordx4 v144, s[8:9]
	s_add_i32 m0, s33, 0xe000
	s_nop 0
	global_load_lds_dwordx4 v146, s[8:9]
	s_waitcnt vmcnt(8)
	s_waitcnt lgkmcnt(0)
	s_barrier
	v_mfma_f32_16x16x32_bf16 v[126:129], v[152:155], v[190:193], v[126:129]
	v_mfma_f32_16x16x32_bf16 v[122:125], v[160:163], v[190:193], v[122:125]
	v_mfma_f32_16x16x32_bf16 v[110:113], v[152:155], v[198:201], v[110:113]
	v_mfma_f32_16x16x32_bf16 v[106:109], v[160:163], v[198:201], v[106:109]
	v_mfma_f32_16x16x32_bf16 v[94:97], v[152:155], v[206:209], v[94:97]
	v_mfma_f32_16x16x32_bf16 v[90:93], v[160:163], v[206:209], v[90:93]
	v_mfma_f32_16x16x32_bf16 v[78:81], v[152:155], v[214:217], v[78:81]
	v_mfma_f32_16x16x32_bf16 v[74:77], v[160:163], v[214:217], v[74:77]
	v_mfma_f32_16x16x32_bf16 v[126:129], v[156:159], v[194:197], v[126:129]
	v_mfma_f32_16x16x32_bf16 v[122:125], v[164:167], v[194:197], v[122:125]
	v_mfma_f32_16x16x32_bf16 v[110:113], v[156:159], v[202:205], v[110:113]
	v_mfma_f32_16x16x32_bf16 v[106:109], v[164:167], v[202:205], v[106:109]
	v_mfma_f32_16x16x32_bf16 v[94:97], v[156:159], v[210:213], v[94:97]
	v_mfma_f32_16x16x32_bf16 v[90:93], v[164:167], v[210:213], v[90:93]
	v_mfma_f32_16x16x32_bf16 v[78:81], v[156:159], v[218:221], v[78:81]
	v_mfma_f32_16x16x32_bf16 v[74:77], v[164:167], v[218:221], v[74:77]
	v_mfma_f32_16x16x32_bf16 v[118:121], v[168:171], v[190:193], v[118:121]
	v_mfma_f32_16x16x32_bf16 v[114:117], v[176:179], v[190:193], v[114:117]
	v_mfma_f32_16x16x32_bf16 v[102:105], v[168:171], v[198:201], v[102:105]
	v_mfma_f32_16x16x32_bf16 v[98:101], v[176:179], v[198:201], v[98:101]
	v_mfma_f32_16x16x32_bf16 v[86:89], v[168:171], v[206:209], v[86:89]
	v_mfma_f32_16x16x32_bf16 v[82:85], v[176:179], v[206:209], v[82:85]
	v_mfma_f32_16x16x32_bf16 v[70:73], v[168:171], v[214:217], v[70:73]
	v_mfma_f32_16x16x32_bf16 v[66:69], v[176:179], v[214:217], v[66:69]
	v_mfma_f32_16x16x32_bf16 v[118:121], v[172:175], v[194:197], v[118:121]
	v_mfma_f32_16x16x32_bf16 v[114:117], v[186:189], v[194:197], v[114:117]
	v_mfma_f32_16x16x32_bf16 v[102:105], v[172:175], v[202:205], v[102:105]
	v_mfma_f32_16x16x32_bf16 v[98:101], v[186:189], v[202:205], v[98:101]
	v_mfma_f32_16x16x32_bf16 v[86:89], v[172:175], v[210:213], v[86:89]
	v_mfma_f32_16x16x32_bf16 v[82:85], v[186:189], v[210:213], v[82:85]
	v_mfma_f32_16x16x32_bf16 v[70:73], v[172:175], v[218:221], v[70:73]
	v_mfma_f32_16x16x32_bf16 v[66:69], v[186:189], v[218:221], v[66:69]
	s_barrier
	s_add_i32 s48, s63, s25
	s_mov_b32 m0, s48
	ds_read_b128 v[190:193], v184 offset:16384
	ds_read_b128 v[194:197], v184 offset:17408
	ds_read_b128 v[198:201], v184 offset:18432
	ds_read_b128 v[202:205], v184 offset:19456
	ds_read_b128 v[206:209], v184 offset:20480
	ds_read_b128 v[210:213], v184 offset:21504
	ds_read_b128 v[214:217], v184 offset:22528
	ds_read_b128 v[218:221], v184 offset:23552
	global_load_lds_dwordx4 v132, s[40:41]
	s_add_i32 m0, s48, 0x2000
	s_add_u32 s48, s40, 0x4000
	s_addc_u32 s49, s41, 0
	s_add_i32 s50, s64, s25
	global_load_lds_dwordx4 v136, s[40:41]
	s_mov_b32 m0, s50
	s_nop 0
	global_load_lds_dwordx4 v132, s[48:49]
	s_add_i32 m0, s50, 0x2000
	s_nop 0
	global_load_lds_dwordx4 v136, s[48:49]
	s_waitcnt vmcnt(6)
	s_waitcnt lgkmcnt(0)
	s_barrier
	v_mfma_f32_16x16x32_bf16 v[62:65], v[152:155], v[190:193], v[62:65]
	v_mfma_f32_16x16x32_bf16 v[58:61], v[160:163], v[190:193], v[58:61]
	v_mfma_f32_16x16x32_bf16 v[46:49], v[152:155], v[198:201], v[46:49]
	v_mfma_f32_16x16x32_bf16 v[42:45], v[160:163], v[198:201], v[42:45]
	v_mfma_f32_16x16x32_bf16 v[30:33], v[152:155], v[206:209], v[30:33]
	v_mfma_f32_16x16x32_bf16 v[26:29], v[160:163], v[206:209], v[26:29]
	v_mfma_f32_16x16x32_bf16 v[14:17], v[152:155], v[214:217], v[14:17]
	v_mfma_f32_16x16x32_bf16 v[10:13], v[160:163], v[214:217], v[10:13]
	v_mfma_f32_16x16x32_bf16 v[62:65], v[156:159], v[194:197], v[62:65]
	v_mfma_f32_16x16x32_bf16 v[58:61], v[164:167], v[194:197], v[58:61]
	v_mfma_f32_16x16x32_bf16 v[46:49], v[156:159], v[202:205], v[46:49]
	v_mfma_f32_16x16x32_bf16 v[42:45], v[164:167], v[202:205], v[42:45]
	v_mfma_f32_16x16x32_bf16 v[30:33], v[156:159], v[210:213], v[30:33]
	v_mfma_f32_16x16x32_bf16 v[26:29], v[164:167], v[210:213], v[26:29]
	v_mfma_f32_16x16x32_bf16 v[14:17], v[156:159], v[218:221], v[14:17]
	v_mfma_f32_16x16x32_bf16 v[10:13], v[164:167], v[218:221], v[10:13]
	v_mfma_f32_16x16x32_bf16 v[54:57], v[168:171], v[190:193], v[54:57]
	v_mfma_f32_16x16x32_bf16 v[50:53], v[176:179], v[190:193], v[50:53]
	v_mfma_f32_16x16x32_bf16 v[38:41], v[168:171], v[198:201], v[38:41]
	v_mfma_f32_16x16x32_bf16 v[34:37], v[176:179], v[198:201], v[34:37]
	v_mfma_f32_16x16x32_bf16 v[22:25], v[168:171], v[206:209], v[22:25]
	v_mfma_f32_16x16x32_bf16 v[18:21], v[176:179], v[206:209], v[18:21]
	v_mfma_f32_16x16x32_bf16 v[6:9], v[168:171], v[214:217], v[6:9]
	v_mfma_f32_16x16x32_bf16 v[2:5], v[176:179], v[214:217], v[2:5]
	v_mfma_f32_16x16x32_bf16 v[54:57], v[172:175], v[194:197], v[54:57]
	v_mfma_f32_16x16x32_bf16 v[50:53], v[186:189], v[194:197], v[50:53]
	v_mfma_f32_16x16x32_bf16 v[38:41], v[172:175], v[202:205], v[38:41]
	v_mfma_f32_16x16x32_bf16 v[34:37], v[186:189], v[202:205], v[34:37]
	v_mfma_f32_16x16x32_bf16 v[22:25], v[172:175], v[210:213], v[22:25]
	v_mfma_f32_16x16x32_bf16 v[18:21], v[186:189], v[210:213], v[18:21]
	v_mfma_f32_16x16x32_bf16 v[6:9], v[172:175], v[218:221], v[6:9]
	v_mfma_f32_16x16x32_bf16 v[2:5], v[186:189], v[218:221], v[2:5]
	s_barrier
; #define PG8_STAGE(bufoff, gbase, voff) do { _Pragma("unroll") for (int _i = 0; _i < 2; ++_i) \
;         __builtin_amdgcn_global_load_lds((const unsigned*)((const char*)(gbase) + (voff)[_i]), (LAS unsigned*)(lds + (bufoff) + ldsw + _i * 8192), 16, 0, 0); } while (0)
; #define PG8_LDA(dst, b, h) do { _Pragma("unroll") for (int m = 0; m < 4; ++m) _Pragma("unroll") for (int k = 0; k < 2; ++k) dst[m][k] = *(const LAS bf16x8*)(lds + PG8_SA(b, h) + aoff + m * 2048 + k * 1024); } while (0)
; #define PG8_LDB(dst, b, h) do { _Pragma("unroll") for (int n = 0; n < 2; ++n) _Pragma("unroll") for (int k = 0; k < 2; ++k) dst[n][k] = *(const LAS bf16x8*)(lds + PG8_SB(b, h) + boff + n * 2048 + k * 1024); } while (0)
; #define PG8_WAIT_V(n) asm volatile("s_waitcnt vmcnt(" #n ")" ::: "memory")
; #define PG8_WAIT_L(n) asm volatile("s_waitcnt lgkmcnt(" #n ")" ::: "memory")
; #define PG8_BAR __builtin_amdgcn_s_barrier()
; #define PG8_SCHED __builtin_amdgcn_sched_barrier(0)
; template <class Epi, class Sched, bool I8 = false>
; __device__ __forceinline__ void gemm_phase(LAS unsigned char* lds, const Gemm g, const Sched& S, const Epi& E) {
;     ...
;             PG8_LDB(B0, 1, 0); PG8_LDB(B1, 1, 1); PG8_SCHED; PG8_LDA(At, 1, 0); PG8_STAGE(PG8_SA(0, 1), a2 + hstepA, voffA);
;             PG8_WAIT_V(8); PG8_WAIT_L(0); PG8_BAR; PG8_MMA(0, 0, At, B0); PG8_MMA(0, 1, At, B1); PG8_BAR; PG8_SCHED;
;             PG8_LDA(At, 1, 1); PG8_STAGE(PG8_SB(1, 0), b3, voffB); PG8_STAGE(PG8_SB(1, 1), b3 + hstepB, voffB); PG8_STAGE(PG8_SA(1, 0), a3, voffA);
;             PG8_WAIT_V(8); PG8_WAIT_L(0); PG8_BAR; PG8_MMA(1, 0, At, B0); PG8_MMA(1, 1, At, B1); PG8_BAR; PG8_SCHED;
;         }
	s_add_i32 s48, 0, 0x18000
	v_add_u32_e32 v138, s48, v181
	s_add_i32 s49, 0, 0x1c000
	ds_read_b128 v[152:155], v138
	ds_read_b128 v[156:159], v138 offset:1024
	ds_read_b128 v[160:163], v138 offset:2048
	ds_read_b128 v[164:167], v138 offset:3072
	v_add_u32_e32 v138, s49, v181
	ds_read_b128 v[168:171], v138
	ds_read_b128 v[172:175], v138 offset:1024
	ds_read_b128 v[176:179], v138 offset:2048
	ds_read_b128 v[186:189], v138 offset:3072
	s_mov_b32 m0, s33
	s_nop 0
	global_load_lds_dwordx4 v130, s[42:43]
	s_mov_b32 m0, s52
	s_nop 0
	global_load_lds_dwordx4 v134, s[42:43]
	s_add_u32 s42, s42, 0x4000
	s_addc_u32 s43, s43, 0
	s_mov_b32 m0, s53
	ds_read_b128 v[190:193], v184 offset:32768
	ds_read_b128 v[194:197], v184 offset:33792
	ds_read_b128 v[198:201], v184 offset:34816
	ds_read_b128 v[202:205], v184 offset:35840
	ds_read_b128 v[206:209], v184 offset:36864
	ds_read_b128 v[210:213], v184 offset:37888
	ds_read_b128 v[214:217], v184 offset:38912
	ds_read_b128 v[218:221], v184 offset:39936
	global_load_lds_dwordx4 v130, s[42:43]
	s_mov_b32 m0, s54
	s_nop 0
	global_load_lds_dwordx4 v134, s[42:43]
	s_waitcnt vmcnt(8)
	s_waitcnt lgkmcnt(0)
	s_barrier
	v_mfma_f32_16x16x32_bf16 v[126:129], v[152:155], v[190:193], v[126:129]
	v_mfma_f32_16x16x32_bf16 v[122:125], v[160:163], v[190:193], v[122:125]
	v_mfma_f32_16x16x32_bf16 v[110:113], v[152:155], v[198:201], v[110:113]
	v_mfma_f32_16x16x32_bf16 v[106:109], v[160:163], v[198:201], v[106:109]
	v_mfma_f32_16x16x32_bf16 v[94:97], v[152:155], v[206:209], v[94:97]
	v_mfma_f32_16x16x32_bf16 v[90:93], v[160:163], v[206:209], v[90:93]
	v_mfma_f32_16x16x32_bf16 v[78:81], v[152:155], v[214:217], v[78:81]
	v_mfma_f32_16x16x32_bf16 v[74:77], v[160:163], v[214:217], v[74:77]
	v_mfma_f32_16x16x32_bf16 v[126:129], v[156:159], v[194:197], v[126:129]
	v_mfma_f32_16x16x32_bf16 v[122:125], v[164:167], v[194:197], v[122:125]
	v_mfma_f32_16x16x32_bf16 v[110:113], v[156:159], v[202:205], v[110:113]
	v_mfma_f32_16x16x32_bf16 v[106:109], v[164:167], v[202:205], v[106:109]
	v_mfma_f32_16x16x32_bf16 v[94:97], v[156:159], v[210:213], v[94:97]
	v_mfma_f32_16x16x32_bf16 v[90:93], v[164:167], v[210:213], v[90:93]
	v_mfma_f32_16x16x32_bf16 v[78:81], v[156:159], v[218:221], v[78:81]
	v_mfma_f32_16x16x32_bf16 v[74:77], v[164:167], v[218:221], v[74:77]
	v_mfma_f32_16x16x32_bf16 v[118:121], v[168:171], v[190:193], v[118:121]
	v_mfma_f32_16x16x32_bf16 v[114:117], v[176:179], v[190:193], v[114:117]
	v_mfma_f32_16x16x32_bf16 v[102:105], v[168:171], v[198:201], v[102:105]
	v_mfma_f32_16x16x32_bf16 v[98:101], v[176:179], v[198:201], v[98:101]
	v_mfma_f32_16x16x32_bf16 v[86:89], v[168:171], v[206:209], v[86:89]
	v_mfma_f32_16x16x32_bf16 v[82:85], v[176:179], v[206:209], v[82:85]
	v_mfma_f32_16x16x32_bf16 v[70:73], v[168:171], v[214:217], v[70:73]
	v_mfma_f32_16x16x32_bf16 v[66:69], v[176:179], v[214:217], v[66:69]
	v_mfma_f32_16x16x32_bf16 v[118:121], v[172:175], v[194:197], v[118:121]
	v_mfma_f32_16x16x32_bf16 v[114:117], v[186:189], v[194:197], v[114:117]
	v_mfma_f32_16x16x32_bf16 v[102:105], v[172:175], v[202:205], v[102:105]
	v_mfma_f32_16x16x32_bf16 v[98:101], v[186:189], v[202:205], v[98:101]
	v_mfma_f32_16x16x32_bf16 v[86:89], v[172:175], v[210:213], v[86:89]
	v_mfma_f32_16x16x32_bf16 v[82:85], v[186:189], v[210:213], v[82:85]
	v_mfma_f32_16x16x32_bf16 v[70:73], v[172:175], v[218:221], v[70:73]
	v_mfma_f32_16x16x32_bf16 v[66:69], v[186:189], v[218:221], v[66:69]
	s_barrier
	s_add_u32 s42, s40, 0x8000
	s_addc_u32 s43, s41, 0
	s_add_i32 s48, s48, s25
	s_mov_b32 m0, s48
	ds_read_b128 v[190:193], v184 offset:49152
	ds_read_b128 v[194:197], v184 offset:50176
	ds_read_b128 v[198:201], v184 offset:51200
	ds_read_b128 v[202:205], v184 offset:52224
	ds_read_b128 v[206:209], v184 offset:53248
	ds_read_b128 v[210:213], v184 offset:54272
	ds_read_b128 v[214:217], v184 offset:55296
	ds_read_b128 v[218:221], v184 offset:56320
	global_load_lds_dwordx4 v132, s[42:43]
	s_add_i32 m0, s48, 0x2000
	s_add_u32 s40, s40, 0xc000
	v_lshl_add_u64 v[222:223], s[42:43], 0, v[136:137]
	s_addc_u32 s41, s41, 0
	s_add_i32 s42, s49, s25
	global_load_lds_dwordx4 v[222:223], off
	s_mov_b32 m0, s42
	s_nop 0
	global_load_lds_dwordx4 v132, s[40:41]
	s_add_i32 m0, s42, 0x2000
	s_nop 0
	global_load_lds_dwordx4 v136, s[40:41]
	s_waitcnt vmcnt(6)
	s_waitcnt lgkmcnt(0)
	s_barrier
	v_mfma_f32_16x16x32_bf16 v[62:65], v[152:155], v[190:193], v[62:65]
	v_mfma_f32_16x16x32_bf16 v[58:61], v[160:163], v[190:193], v[58:61]
	v_mfma_f32_16x16x32_bf16 v[46:49], v[152:155], v[198:201], v[46:49]
	v_mfma_f32_16x16x32_bf16 v[42:45], v[160:163], v[198:201], v[42:45]
	v_mfma_f32_16x16x32_bf16 v[30:33], v[152:155], v[206:209], v[30:33]
	v_mfma_f32_16x16x32_bf16 v[26:29], v[160:163], v[206:209], v[26:29]
	v_mfma_f32_16x16x32_bf16 v[14:17], v[152:155], v[214:217], v[14:17]
	v_mfma_f32_16x16x32_bf16 v[10:13], v[160:163], v[214:217], v[10:13]
	v_mfma_f32_16x16x32_bf16 v[62:65], v[156:159], v[194:197], v[62:65]
	v_mfma_f32_16x16x32_bf16 v[58:61], v[164:167], v[194:197], v[58:61]
	v_mfma_f32_16x16x32_bf16 v[46:49], v[156:159], v[202:205], v[46:49]
	v_mfma_f32_16x16x32_bf16 v[42:45], v[164:167], v[202:205], v[42:45]
	v_mfma_f32_16x16x32_bf16 v[30:33], v[156:159], v[210:213], v[30:33]
	v_mfma_f32_16x16x32_bf16 v[26:29], v[164:167], v[210:213], v[26:29]
	v_mfma_f32_16x16x32_bf16 v[14:17], v[156:159], v[218:221], v[14:17]
	v_mfma_f32_16x16x32_bf16 v[10:13], v[164:167], v[218:221], v[10:13]
	v_mfma_f32_16x16x32_bf16 v[54:57], v[168:171], v[190:193], v[54:57]
	v_mfma_f32_16x16x32_bf16 v[50:53], v[176:179], v[190:193], v[50:53]
	v_mfma_f32_16x16x32_bf16 v[38:41], v[168:171], v[198:201], v[38:41]
	v_mfma_f32_16x16x32_bf16 v[34:37], v[176:179], v[198:201], v[34:37]
	v_mfma_f32_16x16x32_bf16 v[22:25], v[168:171], v[206:209], v[22:25]
	v_mfma_f32_16x16x32_bf16 v[18:21], v[176:179], v[206:209], v[18:21]
	v_mfma_f32_16x16x32_bf16 v[6:9], v[168:171], v[214:217], v[6:9]
	v_mfma_f32_16x16x32_bf16 v[2:5], v[176:179], v[214:217], v[2:5]
	v_mfma_f32_16x16x32_bf16 v[54:57], v[172:175], v[194:197], v[54:57]
	v_mfma_f32_16x16x32_bf16 v[50:53], v[186:189], v[194:197], v[50:53]
	v_mfma_f32_16x16x32_bf16 v[38:41], v[172:175], v[202:205], v[38:41]
	v_mfma_f32_16x16x32_bf16 v[34:37], v[186:189], v[202:205], v[34:37]
	v_mfma_f32_16x16x32_bf16 v[22:25], v[172:175], v[210:213], v[22:25]
	v_mfma_f32_16x16x32_bf16 v[18:21], v[186:189], v[210:213], v[18:21]
	v_mfma_f32_16x16x32_bf16 v[6:9], v[172:175], v[218:221], v[6:9]
	v_mfma_f32_16x16x32_bf16 v[2:5], v[186:189], v[218:221], v[2:5]
	s_barrier
	s_add_i32 s47, s47, 2
	s_add_u32 s8, s8, 0x10000
	s_addc_u32 s9, s9, 0
	s_add_u32 s45, s45, 0x10000
	s_addc_u32 s46, s46, 0
	s_cmp_gt_u32 s47, 61
	s_cbranch_scc0 .LBB0_1482
	s_and_b64 vcc, exec, s[20:21]
	s_cbranch_vccz .LBB0_1485
	s_barrier

; #define PG8_STAGE(bufoff, gbase, voff) do { _Pragma("unroll") for (int _i = 0; _i < 2; ++_i) \
;         __builtin_amdgcn_global_load_lds((const unsigned*)((const char*)(gbase) + (voff)[_i]), (LAS unsigned*)(lds + (bufoff) + ldsw + _i * 8192), 16, 0, 0); } while (0)
; #define PG8_LDA(dst, b, h) do { _Pragma("unroll") for (int m = 0; m < 4; ++m) _Pragma("unroll") for (int k = 0; k < 2; ++k) dst[m][k] = *(const LAS bf16x8*)(lds + PG8_SA(b, h) + aoff + m * 2048 + k * 1024); } while (0)
; #define PG8_LDB(dst, b, h) do { _Pragma("unroll") for (int n = 0; n < 2; ++n) _Pragma("unroll") for (int k = 0; k < 2; ++k) dst[n][k] = *(const LAS bf16x8*)(lds + PG8_SB(b, h) + boff + n * 2048 + k * 1024); } while (0)
; #define PG8_WAIT_V(n) asm volatile("s_waitcnt vmcnt(" #n ")" ::: "memory")
; #define PG8_WAIT_L(n) asm volatile("s_waitcnt lgkmcnt(" #n ")" ::: "memory")
; #define PG8_BAR __builtin_amdgcn_s_barrier()
; #define PG8_SCHED __builtin_amdgcn_sched_barrier(0)
; template <class Epi, class Sched, bool I8 = false>
; __device__ __forceinline__ void gemm_phase(LAS unsigned char* lds, const Gemm g, const Sched& S, const Epi& E) {
;     ...
;             const bool last = (t == nt - 2);
;             const char* a1 = cA + (size_t)(t + 1) * kstep;
;             const char* a2 = last ? nA : cA + (size_t)(t + 2) * kstep; const char* b2 = last ? nB : cB + (size_t)(t + 2) * kstep;
;             const char* a3 = a2 + kstep; const char* b3 = b2 + kstep;
;             PG8_LDB(B0, 0, 0); PG8_LDB(B1, 0, 1); PG8_SCHED; PG8_LDA(At, 0, 0); PG8_STAGE(PG8_SA(1, 1), a1 + hstepA, voffA);
;             PG8_WAIT_V(8); PG8_WAIT_L(0); PG8_BAR; PG8_MMA(0, 0, At, B0); PG8_MMA(0, 1, At, B1); PG8_BAR; PG8_SCHED;
;             PG8_LDA(At, 0, 1); PG8_STAGE(PG8_SB(0, 0), b2, voffB); PG8_STAGE(PG8_SB(0, 1), b2 + hstepB, voffB); PG8_STAGE(PG8_SA(0, 0), a2, voffA);
;             PG8_WAIT_V(8); PG8_WAIT_L(0); PG8_BAR; PG8_MMA(1, 0, At, B0); PG8_MMA(1, 1, At, B1); PG8_BAR; PG8_SCHED;
.LBB0_2685:
	ds_read_b128 v[130:133], v166
	ds_read_b128 v[134:137], v166 offset:1024
	ds_read_b128 v[158:161], v166 offset:2048
	ds_read_b128 v[170:173], v166 offset:3072
	ds_read_b128 v[174:177], v167
	ds_read_b128 v[178:181], v167 offset:1024
	ds_read_b128 v[182:185], v167 offset:2048
	ds_read_b128 v[186:189], v167 offset:3072
	s_add_u32 s12, s10, 0x4000
	s_addc_u32 s13, s11, 0
	s_cmp_eq_u32 s45, 4
	s_cselect_b32 s16, s40, s12
	s_cselect_b32 s17, s39, s13
	s_cselect_b32 s14, s42, s43
	s_cselect_b32 s15, s41, s44
	s_add_u32 s12, s16, 0x8000
	s_addc_u32 s13, s17, 0
	s_sub_u32 s98, s10, 0x4000
	s_subb_u32 s99, s11, 0
	s_mov_b32 m0, s33
	s_nop 0
	global_load_lds_dwordx4 v144, s[98:99]
	s_mov_b32 m0, s34
	s_nop 0
	global_load_lds_dwordx4 v140, s[98:99]
	s_add_i32 m0, s26, 0xc000
	ds_read_b128 v[190:193], v168
	ds_read_b128 v[194:197], v168 offset:1024
	ds_read_b128 v[198:201], v168 offset:2048
	ds_read_b128 v[202:205], v168 offset:3072
	ds_read_b128 v[206:209], v168 offset:4096
	ds_read_b128 v[210:213], v168 offset:5120
	ds_read_b128 v[214:217], v168 offset:6144
	ds_read_b128 v[218:221], v168 offset:7168
	global_load_lds_dwordx4 v150, s[10:11]
	s_add_i32 m0, s26, 0xe000
	s_nop 0
	global_load_lds_dwordx4 v152, s[10:11]
	s_waitcnt vmcnt(8)
	s_waitcnt lgkmcnt(0)
	s_barrier
	v_mfma_f32_16x16x32_bf16 v[126:129], v[130:133], v[190:193], v[126:129]
	v_mfma_f32_16x16x32_bf16 v[122:125], v[158:161], v[190:193], v[122:125]
	v_mfma_f32_16x16x32_bf16 v[118:121], v[130:133], v[198:201], v[118:121]
	v_mfma_f32_16x16x32_bf16 v[114:117], v[158:161], v[198:201], v[114:117]
	v_mfma_f32_16x16x32_bf16 v[110:113], v[130:133], v[206:209], v[110:113]
	v_mfma_f32_16x16x32_bf16 v[106:109], v[158:161], v[206:209], v[106:109]
	v_mfma_f32_16x16x32_bf16 v[102:105], v[130:133], v[214:217], v[102:105]
	v_mfma_f32_16x16x32_bf16 v[98:101], v[158:161], v[214:217], v[98:101]
	v_mfma_f32_16x16x32_bf16 v[126:129], v[134:137], v[194:197], v[126:129]
	v_mfma_f32_16x16x32_bf16 v[122:125], v[170:173], v[194:197], v[122:125]
	v_mfma_f32_16x16x32_bf16 v[118:121], v[134:137], v[202:205], v[118:121]
	v_mfma_f32_16x16x32_bf16 v[114:117], v[170:173], v[202:205], v[114:117]
	v_mfma_f32_16x16x32_bf16 v[110:113], v[134:137], v[210:213], v[110:113]
	v_mfma_f32_16x16x32_bf16 v[106:109], v[170:173], v[210:213], v[106:109]
	v_mfma_f32_16x16x32_bf16 v[102:105], v[134:137], v[218:221], v[102:105]
	v_mfma_f32_16x16x32_bf16 v[98:101], v[170:173], v[218:221], v[98:101]
	v_mfma_f32_16x16x32_bf16 v[62:65], v[174:177], v[190:193], v[62:65]
	v_mfma_f32_16x16x32_bf16 v[58:61], v[182:185], v[190:193], v[58:61]
	v_mfma_f32_16x16x32_bf16 v[54:57], v[174:177], v[198:201], v[54:57]
	v_mfma_f32_16x16x32_bf16 v[50:53], v[182:185], v[198:201], v[50:53]
	v_mfma_f32_16x16x32_bf16 v[46:49], v[174:177], v[206:209], v[46:49]
	v_mfma_f32_16x16x32_bf16 v[42:45], v[182:185], v[206:209], v[42:45]
	v_mfma_f32_16x16x32_bf16 v[38:41], v[174:177], v[214:217], v[38:41]
	v_mfma_f32_16x16x32_bf16 v[34:37], v[182:185], v[214:217], v[34:37]
	v_mfma_f32_16x16x32_bf16 v[62:65], v[178:181], v[194:197], v[62:65]
	v_mfma_f32_16x16x32_bf16 v[58:61], v[186:189], v[194:197], v[58:61]
	v_mfma_f32_16x16x32_bf16 v[54:57], v[178:181], v[202:205], v[54:57]
	v_mfma_f32_16x16x32_bf16 v[50:53], v[186:189], v[202:205], v[50:53]
	v_mfma_f32_16x16x32_bf16 v[46:49], v[178:181], v[210:213], v[46:49]
	v_mfma_f32_16x16x32_bf16 v[42:45], v[186:189], v[210:213], v[42:45]
	v_mfma_f32_16x16x32_bf16 v[38:41], v[178:181], v[218:221], v[38:41]
	v_mfma_f32_16x16x32_bf16 v[34:37], v[186:189], v[218:221], v[34:37]
	s_barrier
	s_add_i32 s46, s62, s22
	s_mov_b32 m0, s46
	ds_read_b128 v[190:193], v168 offset:16384
	ds_read_b128 v[194:197], v168 offset:17408
	ds_read_b128 v[198:201], v168 offset:18432
	ds_read_b128 v[202:205], v168 offset:19456
	ds_read_b128 v[206:209], v168 offset:20480
	ds_read_b128 v[210:213], v168 offset:21504
	ds_read_b128 v[214:217], v168 offset:22528
	ds_read_b128 v[218:221], v168 offset:23552
	global_load_lds_dwordx4 v142, s[14:15]
	s_add_i32 m0, s46, 0x2000
	s_add_u32 s46, s14, 0x4000
	s_addc_u32 s47, s15, 0
	s_add_i32 s48, s35, s22
	global_load_lds_dwordx4 v138, s[14:15]
	s_mov_b32 m0, s48
	s_nop 0
	global_load_lds_dwordx4 v142, s[46:47]
	s_add_i32 m0, s48, 0x2000
	s_nop 0
	global_load_lds_dwordx4 v138, s[46:47]
	s_waitcnt vmcnt(6)
	s_waitcnt lgkmcnt(0)
	s_barrier
	v_mfma_f32_16x16x32_bf16 v[94:97], v[130:133], v[190:193], v[94:97]
	v_mfma_f32_16x16x32_bf16 v[90:93], v[158:161], v[190:193], v[90:93]
	v_mfma_f32_16x16x32_bf16 v[86:89], v[130:133], v[198:201], v[86:89]
	v_mfma_f32_16x16x32_bf16 v[82:85], v[158:161], v[198:201], v[82:85]
	v_mfma_f32_16x16x32_bf16 v[78:81], v[130:133], v[206:209], v[78:81]
	v_mfma_f32_16x16x32_bf16 v[74:77], v[158:161], v[206:209], v[74:77]
	v_mfma_f32_16x16x32_bf16 v[70:73], v[130:133], v[214:217], v[70:73]
	v_mfma_f32_16x16x32_bf16 v[66:69], v[158:161], v[214:217], v[66:69]
	v_mfma_f32_16x16x32_bf16 v[94:97], v[134:137], v[194:197], v[94:97]
	v_mfma_f32_16x16x32_bf16 v[90:93], v[170:173], v[194:197], v[90:93]
	v_mfma_f32_16x16x32_bf16 v[86:89], v[134:137], v[202:205], v[86:89]
	v_mfma_f32_16x16x32_bf16 v[82:85], v[170:173], v[202:205], v[82:85]
	v_mfma_f32_16x16x32_bf16 v[78:81], v[134:137], v[210:213], v[78:81]
	v_mfma_f32_16x16x32_bf16 v[74:77], v[170:173], v[210:213], v[74:77]
	v_mfma_f32_16x16x32_bf16 v[70:73], v[134:137], v[218:221], v[70:73]
	v_mfma_f32_16x16x32_bf16 v[66:69], v[170:173], v[218:221], v[66:69]
	v_mfma_f32_16x16x32_bf16 v[30:33], v[174:177], v[190:193], v[30:33]
	v_mfma_f32_16x16x32_bf16 v[26:29], v[182:185], v[190:193], v[26:29]
	v_mfma_f32_16x16x32_bf16 v[22:25], v[174:177], v[198:201], v[22:25]
	v_mfma_f32_16x16x32_bf16 v[18:21], v[182:185], v[198:201], v[18:21]
	v_mfma_f32_16x16x32_bf16 v[14:17], v[174:177], v[206:209], v[14:17]
	v_mfma_f32_16x16x32_bf16 v[10:13], v[182:185], v[206:209], v[10:13]
	v_mfma_f32_16x16x32_bf16 v[6:9], v[174:177], v[214:217], v[6:9]
	v_mfma_f32_16x16x32_bf16 v[2:5], v[182:185], v[214:217], v[2:5]
	v_mfma_f32_16x16x32_bf16 v[30:33], v[178:181], v[194:197], v[30:33]
	v_mfma_f32_16x16x32_bf16 v[26:29], v[186:189], v[194:197], v[26:29]
	v_mfma_f32_16x16x32_bf16 v[22:25], v[178:181], v[202:205], v[22:25]
	v_mfma_f32_16x16x32_bf16 v[18:21], v[186:189], v[202:205], v[18:21]
	v_mfma_f32_16x16x32_bf16 v[14:17], v[178:181], v[210:213], v[14:17]
	v_mfma_f32_16x16x32_bf16 v[10:13], v[186:189], v[210:213], v[10:13]
	v_mfma_f32_16x16x32_bf16 v[6:9], v[178:181], v[218:221], v[6:9]
	v_mfma_f32_16x16x32_bf16 v[2:5], v[186:189], v[218:221], v[2:5]
	s_barrier
; #define PG8_STAGE(bufoff, gbase, voff) do { _Pragma("unroll") for (int _i = 0; _i < 2; ++_i) \
;         __builtin_amdgcn_global_load_lds((const unsigned*)((const char*)(gbase) + (voff)[_i]), (LAS unsigned*)(lds + (bufoff) + ldsw + _i * 8192), 16, 0, 0); } while (0)
; #define PG8_LDA(dst, b, h) do { _Pragma("unroll") for (int m = 0; m < 4; ++m) _Pragma("unroll") for (int k = 0; k < 2; ++k) dst[m][k] = *(const LAS bf16x8*)(lds + PG8_SA(b, h) + aoff + m * 2048 + k * 1024); } while (0)
; #define PG8_LDB(dst, b, h) do { _Pragma("unroll") for (int n = 0; n < 2; ++n) _Pragma("unroll") for (int k = 0; k < 2; ++k) dst[n][k] = *(const LAS bf16x8*)(lds + PG8_SB(b, h) + boff + n * 2048 + k * 1024); } while (0)
; #define PG8_WAIT_V(n) asm volatile("s_waitcnt vmcnt(" #n ")" ::: "memory")
; #define PG8_WAIT_L(n) asm volatile("s_waitcnt lgkmcnt(" #n ")" ::: "memory")
; #define PG8_BAR __builtin_amdgcn_s_barrier()
; #define PG8_SCHED __builtin_amdgcn_sched_barrier(0)
; template <class Epi, class Sched, bool I8 = false>
; __device__ __forceinline__ void gemm_phase(LAS unsigned char* lds, const Gemm g, const Sched& S, const Epi& E) {
;     ...
;             PG8_LDB(B0, 1, 0); PG8_LDB(B1, 1, 1); PG8_SCHED; PG8_LDA(At, 1, 0); PG8_STAGE(PG8_SA(0, 1), a2 + hstepA, voffA);
;             PG8_WAIT_V(8); PG8_WAIT_L(0); PG8_BAR; PG8_MMA(0, 0, At, B0); PG8_MMA(0, 1, At, B1); PG8_BAR; PG8_SCHED;
;             PG8_LDA(At, 1, 1); PG8_STAGE(PG8_SB(1, 0), b3, voffB); PG8_STAGE(PG8_SB(1, 1), b3 + hstepB, voffB); PG8_STAGE(PG8_SA(1, 0), a3, voffA);
;             PG8_WAIT_V(8); PG8_WAIT_L(0); PG8_BAR; PG8_MMA(1, 0, At, B0); PG8_MMA(1, 1, At, B1); PG8_BAR; PG8_SCHED;
;         }
	s_add_i32 s46, 0, 0x18000
	v_add_u32_e32 v155, s46, v165
	s_add_i32 s47, 0, 0x1c000
	ds_read_b128 v[130:133], v155
	ds_read_b128 v[134:137], v155 offset:1024
	ds_read_b128 v[158:161], v155 offset:2048
	ds_read_b128 v[170:173], v155 offset:3072
	v_add_u32_e32 v155, s47, v165
	ds_read_b128 v[174:177], v155
	ds_read_b128 v[178:181], v155 offset:1024
	ds_read_b128 v[182:185], v155 offset:2048
	ds_read_b128 v[186:189], v155 offset:3072
	s_mov_b32 m0, s26
	s_nop 0
	global_load_lds_dwordx4 v144, s[16:17]
	s_mov_b32 m0, s27
	s_nop 0
	global_load_lds_dwordx4 v140, s[16:17]
	s_add_u32 s16, s16, 0x4000
	s_addc_u32 s17, s17, 0
	s_mov_b32 m0, s28
	ds_read_b128 v[190:193], v168 offset:32768
	ds_read_b128 v[194:197], v168 offset:33792
	ds_read_b128 v[198:201], v168 offset:34816
	ds_read_b128 v[202:205], v168 offset:35840
	ds_read_b128 v[206:209], v168 offset:36864
	ds_read_b128 v[210:213], v168 offset:37888
	ds_read_b128 v[214:217], v168 offset:38912
	ds_read_b128 v[218:221], v168 offset:39936
	global_load_lds_dwordx4 v144, s[16:17]
	s_mov_b32 m0, s29
	s_nop 0
	global_load_lds_dwordx4 v140, s[16:17]
	s_waitcnt vmcnt(8)
	s_waitcnt lgkmcnt(0)
	s_barrier
	v_mfma_f32_16x16x32_bf16 v[126:129], v[130:133], v[190:193], v[126:129]
	v_mfma_f32_16x16x32_bf16 v[122:125], v[158:161], v[190:193], v[122:125]
	v_mfma_f32_16x16x32_bf16 v[118:121], v[130:133], v[198:201], v[118:121]
	v_mfma_f32_16x16x32_bf16 v[114:117], v[158:161], v[198:201], v[114:117]
	v_mfma_f32_16x16x32_bf16 v[110:113], v[130:133], v[206:209], v[110:113]
	v_mfma_f32_16x16x32_bf16 v[106:109], v[158:161], v[206:209], v[106:109]
	v_mfma_f32_16x16x32_bf16 v[102:105], v[130:133], v[214:217], v[102:105]
	v_mfma_f32_16x16x32_bf16 v[98:101], v[158:161], v[214:217], v[98:101]
	v_mfma_f32_16x16x32_bf16 v[126:129], v[134:137], v[194:197], v[126:129]
	v_mfma_f32_16x16x32_bf16 v[122:125], v[170:173], v[194:197], v[122:125]
	v_mfma_f32_16x16x32_bf16 v[118:121], v[134:137], v[202:205], v[118:121]
	v_mfma_f32_16x16x32_bf16 v[114:117], v[170:173], v[202:205], v[114:117]
	v_mfma_f32_16x16x32_bf16 v[110:113], v[134:137], v[210:213], v[110:113]
	v_mfma_f32_16x16x32_bf16 v[106:109], v[170:173], v[210:213], v[106:109]
	v_mfma_f32_16x16x32_bf16 v[102:105], v[134:137], v[218:221], v[102:105]
	v_mfma_f32_16x16x32_bf16 v[98:101], v[170:173], v[218:221], v[98:101]
	v_mfma_f32_16x16x32_bf16 v[62:65], v[174:177], v[190:193], v[62:65]
	v_mfma_f32_16x16x32_bf16 v[58:61], v[182:185], v[190:193], v[58:61]
	v_mfma_f32_16x16x32_bf16 v[54:57], v[174:177], v[198:201], v[54:57]
	v_mfma_f32_16x16x32_bf16 v[50:53], v[182:185], v[198:201], v[50:53]
	v_mfma_f32_16x16x32_bf16 v[46:49], v[174:177], v[206:209], v[46:49]
	v_mfma_f32_16x16x32_bf16 v[42:45], v[182:185], v[206:209], v[42:45]
	v_mfma_f32_16x16x32_bf16 v[38:41], v[174:177], v[214:217], v[38:41]
	v_mfma_f32_16x16x32_bf16 v[34:37], v[182:185], v[214:217], v[34:37]
	v_mfma_f32_16x16x32_bf16 v[62:65], v[178:181], v[194:197], v[62:65]
	v_mfma_f32_16x16x32_bf16 v[58:61], v[186:189], v[194:197], v[58:61]
	v_mfma_f32_16x16x32_bf16 v[54:57], v[178:181], v[202:205], v[54:57]
	v_mfma_f32_16x16x32_bf16 v[50:53], v[186:189], v[202:205], v[50:53]
	v_mfma_f32_16x16x32_bf16 v[46:49], v[178:181], v[210:213], v[46:49]
	v_mfma_f32_16x16x32_bf16 v[42:45], v[186:189], v[210:213], v[42:45]
	v_mfma_f32_16x16x32_bf16 v[38:41], v[178:181], v[218:221], v[38:41]
	v_mfma_f32_16x16x32_bf16 v[34:37], v[186:189], v[218:221], v[34:37]
	s_barrier
	s_add_u32 s16, s14, 0x8000
	s_addc_u32 s17, s15, 0
	s_add_i32 s46, s46, s22
	s_mov_b32 m0, s46
	ds_read_b128 v[190:193], v168 offset:49152
	ds_read_b128 v[194:197], v168 offset:50176
	ds_read_b128 v[198:201], v168 offset:51200
	ds_read_b128 v[202:205], v168 offset:52224
	ds_read_b128 v[206:209], v168 offset:53248
	ds_read_b128 v[210:213], v168 offset:54272
	ds_read_b128 v[214:217], v168 offset:55296
	ds_read_b128 v[218:221], v168 offset:56320
	global_load_lds_dwordx4 v142, s[16:17]
	s_add_i32 m0, s46, 0x2000
	s_add_u32 s14, s14, 0xc000
	v_lshl_add_u64 v[162:163], s[16:17], 0, v[138:139]
	s_addc_u32 s15, s15, 0
	s_add_i32 s16, s47, s22
	global_load_lds_dwordx4 v[162:163], off
	s_mov_b32 m0, s16
	s_nop 0
	global_load_lds_dwordx4 v142, s[14:15]
	s_add_i32 m0, s16, 0x2000
	s_nop 0
	global_load_lds_dwordx4 v138, s[14:15]
	s_waitcnt vmcnt(6)
	s_waitcnt lgkmcnt(0)
	s_barrier
	v_mfma_f32_16x16x32_bf16 v[94:97], v[130:133], v[190:193], v[94:97]
	v_mfma_f32_16x16x32_bf16 v[90:93], v[158:161], v[190:193], v[90:93]
	v_mfma_f32_16x16x32_bf16 v[86:89], v[130:133], v[198:201], v[86:89]
	v_mfma_f32_16x16x32_bf16 v[82:85], v[158:161], v[198:201], v[82:85]
	v_mfma_f32_16x16x32_bf16 v[78:81], v[130:133], v[206:209], v[78:81]
	v_mfma_f32_16x16x32_bf16 v[74:77], v[158:161], v[206:209], v[74:77]
	v_mfma_f32_16x16x32_bf16 v[70:73], v[130:133], v[214:217], v[70:73]
	v_mfma_f32_16x16x32_bf16 v[66:69], v[158:161], v[214:217], v[66:69]
	v_mfma_f32_16x16x32_bf16 v[94:97], v[134:137], v[194:197], v[94:97]
	v_mfma_f32_16x16x32_bf16 v[90:93], v[170:173], v[194:197], v[90:93]
	v_mfma_f32_16x16x32_bf16 v[86:89], v[134:137], v[202:205], v[86:89]
	v_mfma_f32_16x16x32_bf16 v[82:85], v[170:173], v[202:205], v[82:85]
	v_mfma_f32_16x16x32_bf16 v[78:81], v[134:137], v[210:213], v[78:81]
	v_mfma_f32_16x16x32_bf16 v[74:77], v[170:173], v[210:213], v[74:77]
	v_mfma_f32_16x16x32_bf16 v[70:73], v[134:137], v[218:221], v[70:73]
	v_mfma_f32_16x16x32_bf16 v[66:69], v[170:173], v[218:221], v[66:69]
	v_mfma_f32_16x16x32_bf16 v[30:33], v[174:177], v[190:193], v[30:33]
	v_mfma_f32_16x16x32_bf16 v[26:29], v[182:185], v[190:193], v[26:29]
	v_mfma_f32_16x16x32_bf16 v[22:25], v[174:177], v[198:201], v[22:25]
	v_mfma_f32_16x16x32_bf16 v[18:21], v[182:185], v[198:201], v[18:21]
	v_mfma_f32_16x16x32_bf16 v[14:17], v[174:177], v[206:209], v[14:17]
	v_mfma_f32_16x16x32_bf16 v[10:13], v[182:185], v[206:209], v[10:13]
	v_mfma_f32_16x16x32_bf16 v[6:9], v[174:177], v[214:217], v[6:9]
	v_mfma_f32_16x16x32_bf16 v[2:5], v[182:185], v[214:217], v[2:5]
	v_mfma_f32_16x16x32_bf16 v[30:33], v[178:181], v[194:197], v[30:33]
	v_mfma_f32_16x16x32_bf16 v[26:29], v[186:189], v[194:197], v[26:29]
	v_mfma_f32_16x16x32_bf16 v[22:25], v[178:181], v[202:205], v[22:25]
	v_mfma_f32_16x16x32_bf16 v[18:21], v[186:189], v[202:205], v[18:21]
	v_mfma_f32_16x16x32_bf16 v[14:17], v[178:181], v[210:213], v[14:17]
	v_mfma_f32_16x16x32_bf16 v[10:13], v[186:189], v[210:213], v[10:13]
	v_mfma_f32_16x16x32_bf16 v[6:9], v[178:181], v[218:221], v[6:9]
	v_mfma_f32_16x16x32_bf16 v[2:5], v[186:189], v[218:221], v[2:5]
	s_barrier
	s_add_i32 s45, s45, 2
	s_add_u32 s10, s10, 0x10000
	s_addc_u32 s11, s11, 0
	s_add_u32 s43, s43, 0x10000
	s_addc_u32 s44, s44, 0
	s_cmp_gt_u32 s45, 5
	s_cbranch_scc0 .LBB0_2685
	s_and_b64 vcc, exec, s[6:7]
	s_cbranch_vccz .LBB0_2688
	s_barrier

; #define PG8_STAGE(bufoff, gbase, voff) do { _Pragma("unroll") for (int _i = 0; _i < 2; ++_i) \
;         __builtin_amdgcn_global_load_lds((const unsigned*)((const char*)(gbase) + (voff)[_i]), (LAS unsigned*)(lds + (bufoff) + ldsw + _i * 8192), 16, 0, 0); } while (0)
; #define PG8_LDA(dst, b, h) do { _Pragma("unroll") for (int m = 0; m < 4; ++m) _Pragma("unroll") for (int k = 0; k < 2; ++k) dst[m][k] = *(const LAS bf16x8*)(lds + PG8_SA(b, h) + aoff + m * 2048 + k * 1024); } while (0)
; #define PG8_LDB(dst, b, h) do { _Pragma("unroll") for (int n = 0; n < 2; ++n) _Pragma("unroll") for (int k = 0; k < 2; ++k) dst[n][k] = *(const LAS bf16x8*)(lds + PG8_SB(b, h) + boff + n * 2048 + k * 1024); } while (0)
; #define PG8_WAIT_V(n) asm volatile("s_waitcnt vmcnt(" #n ")" ::: "memory")
; #define PG8_WAIT_L(n) asm volatile("s_waitcnt lgkmcnt(" #n ")" ::: "memory")
; #define PG8_BAR __builtin_amdgcn_s_barrier()
; #define PG8_SCHED __builtin_amdgcn_sched_barrier(0)
; template <class Epi, class Sched, bool I8 = false>
; __device__ __forceinline__ void gemm_phase(LAS unsigned char* lds, const Gemm g, const Sched& S, const Epi& E) {
;     ...
;             const bool last = (t == nt - 2);
;             const char* a1 = cA + (size_t)(t + 1) * kstep;
;             const char* a2 = last ? nA : cA + (size_t)(t + 2) * kstep; const char* b2 = last ? nB : cB + (size_t)(t + 2) * kstep;
;             const char* a3 = a2 + kstep; const char* b3 = b2 + kstep;
;             PG8_LDB(B0, 0, 0); PG8_LDB(B1, 0, 1); PG8_SCHED; PG8_LDA(At, 0, 0); PG8_STAGE(PG8_SA(1, 1), a1 + hstepA, voffA);
;             PG8_WAIT_V(8); PG8_WAIT_L(0); PG8_BAR; PG8_MMA(0, 0, At, B0); PG8_MMA(0, 1, At, B1); PG8_BAR; PG8_SCHED;
;             PG8_LDA(At, 0, 1); PG8_STAGE(PG8_SB(0, 0), b2, voffB); PG8_STAGE(PG8_SB(0, 1), b2 + hstepB, voffB); PG8_STAGE(PG8_SA(0, 0), a2, voffA);
;             PG8_WAIT_V(8); PG8_WAIT_L(0); PG8_BAR; PG8_MMA(1, 0, At, B0); PG8_MMA(1, 1, At, B1); PG8_BAR; PG8_SCHED;
.LBB0_3744:
	ds_read_b128 v[130:133], v231
	ds_read_b128 v[134:137], v231 offset:1024
	ds_read_b128 v[138:141], v231 offset:2048
	ds_read_b128 v[142:145], v231 offset:3072
	ds_read_b128 v[146:149], v232
	ds_read_b128 v[150:153], v232 offset:1024
	ds_read_b128 v[154:157], v232 offset:2048
	ds_read_b128 v[158:161], v232 offset:3072
	s_add_u32 s34, s30, 0x4000
	s_addc_u32 s35, s31, 0
	s_cmp_eq_u32 s59, 60
	s_cselect_b32 s38, s23, s34
	s_cselect_b32 s39, s5, s35
	s_cselect_b32 s36, s29, s57
	s_cselect_b32 s37, s21, s58
	s_add_u32 s34, s38, 0x8000
	s_addc_u32 s35, s39, 0
	s_sub_u32 s98, s30, 0x4000
	s_subb_u32 s99, s31, 0
	s_mov_b32 m0, s51
	s_nop 0
	global_load_lds_dwordx4 v194, s[98:99]
	s_mov_b32 m0, s52
	s_nop 0
	global_load_lds_dwordx4 v198, s[98:99]
	s_add_i32 m0, s44, 0xc000
	ds_read_b128 v[162:165], v233
	ds_read_b128 v[166:169], v233 offset:1024
	ds_read_b128 v[170:173], v233 offset:2048
	ds_read_b128 v[174:177], v233 offset:3072
	ds_read_b128 v[178:181], v233 offset:4096
	ds_read_b128 v[182:185], v233 offset:5120
	ds_read_b128 v[186:189], v233 offset:6144
	ds_read_b128 v[190:193], v233 offset:7168
	global_load_lds_dwordx4 v204, s[30:31]
	s_add_i32 m0, s44, 0xe000
	s_nop 0
	global_load_lds_dwordx4 v206, s[30:31]
	s_waitcnt vmcnt(8)
	s_waitcnt lgkmcnt(0)
	s_barrier
	v_mfma_f32_16x16x32_bf16 v[126:129], v[130:133], v[162:165], v[126:129]
	v_mfma_f32_16x16x32_bf16 v[122:125], v[138:141], v[162:165], v[122:125]
	v_mfma_f32_16x16x32_bf16 v[118:121], v[130:133], v[170:173], v[118:121]
	v_mfma_f32_16x16x32_bf16 v[110:113], v[138:141], v[170:173], v[110:113]
	v_mfma_f32_16x16x32_bf16 v[102:105], v[130:133], v[178:181], v[102:105]
	v_mfma_f32_16x16x32_bf16 v[94:97], v[138:141], v[178:181], v[94:97]
	v_mfma_f32_16x16x32_bf16 v[86:89], v[130:133], v[186:189], v[86:89]
	v_mfma_f32_16x16x32_bf16 v[78:81], v[138:141], v[186:189], v[78:81]
	v_mfma_f32_16x16x32_bf16 v[126:129], v[134:137], v[166:169], v[126:129]
	v_mfma_f32_16x16x32_bf16 v[122:125], v[142:145], v[166:169], v[122:125]
	v_mfma_f32_16x16x32_bf16 v[118:121], v[134:137], v[174:177], v[118:121]
	v_mfma_f32_16x16x32_bf16 v[110:113], v[142:145], v[174:177], v[110:113]
	v_mfma_f32_16x16x32_bf16 v[102:105], v[134:137], v[182:185], v[102:105]
	v_mfma_f32_16x16x32_bf16 v[94:97], v[142:145], v[182:185], v[94:97]
	v_mfma_f32_16x16x32_bf16 v[86:89], v[134:137], v[190:193], v[86:89]
	v_mfma_f32_16x16x32_bf16 v[78:81], v[142:145], v[190:193], v[78:81]
	v_mfma_f32_16x16x32_bf16 v[114:117], v[146:149], v[162:165], v[114:117]
	v_mfma_f32_16x16x32_bf16 v[106:109], v[154:157], v[162:165], v[106:109]
	v_mfma_f32_16x16x32_bf16 v[98:101], v[146:149], v[170:173], v[98:101]
	v_mfma_f32_16x16x32_bf16 v[90:93], v[154:157], v[170:173], v[90:93]
	v_mfma_f32_16x16x32_bf16 v[82:85], v[146:149], v[178:181], v[82:85]
	v_mfma_f32_16x16x32_bf16 v[74:77], v[154:157], v[178:181], v[74:77]
	v_mfma_f32_16x16x32_bf16 v[70:73], v[146:149], v[186:189], v[70:73]
	v_mfma_f32_16x16x32_bf16 v[66:69], v[154:157], v[186:189], v[66:69]
	v_mfma_f32_16x16x32_bf16 v[114:117], v[150:153], v[166:169], v[114:117]
	v_mfma_f32_16x16x32_bf16 v[106:109], v[158:161], v[166:169], v[106:109]
	v_mfma_f32_16x16x32_bf16 v[98:101], v[150:153], v[174:177], v[98:101]
	v_mfma_f32_16x16x32_bf16 v[90:93], v[158:161], v[174:177], v[90:93]
	v_mfma_f32_16x16x32_bf16 v[82:85], v[150:153], v[182:185], v[82:85]
	v_mfma_f32_16x16x32_bf16 v[74:77], v[158:161], v[182:185], v[74:77]
	v_mfma_f32_16x16x32_bf16 v[70:73], v[150:153], v[190:193], v[70:73]
	v_mfma_f32_16x16x32_bf16 v[66:69], v[158:161], v[190:193], v[66:69]
	s_barrier
	s_add_i32 s60, s55, s43
	s_mov_b32 m0, s60
	ds_read_b128 v[162:165], v233 offset:16384
	ds_read_b128 v[166:169], v233 offset:17408
	ds_read_b128 v[170:173], v233 offset:18432
	ds_read_b128 v[174:177], v233 offset:19456
	ds_read_b128 v[178:181], v233 offset:20480
	ds_read_b128 v[182:185], v233 offset:21504
	ds_read_b128 v[186:189], v233 offset:22528
	ds_read_b128 v[190:193], v233 offset:23552
	global_load_lds_dwordx4 v196, s[36:37]
	s_add_i32 m0, s60, 0x2000
	s_add_u32 s60, s36, 0x4000
	s_addc_u32 s61, s37, 0
	s_add_i32 s62, s56, s43
	global_load_lds_dwordx4 v200, s[36:37]
	s_mov_b32 m0, s62
	s_nop 0
	global_load_lds_dwordx4 v196, s[60:61]
	s_add_i32 m0, s62, 0x2000
	s_nop 0
	global_load_lds_dwordx4 v200, s[60:61]
	s_waitcnt vmcnt(6)
	s_waitcnt lgkmcnt(0)
	s_barrier
	v_mfma_f32_16x16x32_bf16 v[62:65], v[130:133], v[162:165], v[62:65]
	v_mfma_f32_16x16x32_bf16 v[58:61], v[138:141], v[162:165], v[58:61]
	v_mfma_f32_16x16x32_bf16 v[54:57], v[130:133], v[170:173], v[54:57]
	v_mfma_f32_16x16x32_bf16 v[46:49], v[138:141], v[170:173], v[46:49]
	v_mfma_f32_16x16x32_bf16 v[38:41], v[130:133], v[178:181], v[38:41]
	v_mfma_f32_16x16x32_bf16 v[30:33], v[138:141], v[178:181], v[30:33]
	v_mfma_f32_16x16x32_bf16 v[22:25], v[130:133], v[186:189], v[22:25]
	v_mfma_f32_16x16x32_bf16 v[14:17], v[138:141], v[186:189], v[14:17]
	v_mfma_f32_16x16x32_bf16 v[62:65], v[134:137], v[166:169], v[62:65]
	v_mfma_f32_16x16x32_bf16 v[58:61], v[142:145], v[166:169], v[58:61]
	v_mfma_f32_16x16x32_bf16 v[54:57], v[134:137], v[174:177], v[54:57]
	v_mfma_f32_16x16x32_bf16 v[46:49], v[142:145], v[174:177], v[46:49]
	v_mfma_f32_16x16x32_bf16 v[38:41], v[134:137], v[182:185], v[38:41]
	v_mfma_f32_16x16x32_bf16 v[30:33], v[142:145], v[182:185], v[30:33]
	v_mfma_f32_16x16x32_bf16 v[22:25], v[134:137], v[190:193], v[22:25]
	v_mfma_f32_16x16x32_bf16 v[14:17], v[142:145], v[190:193], v[14:17]
	v_mfma_f32_16x16x32_bf16 v[50:53], v[146:149], v[162:165], v[50:53]
	v_mfma_f32_16x16x32_bf16 v[42:45], v[154:157], v[162:165], v[42:45]
	v_mfma_f32_16x16x32_bf16 v[34:37], v[146:149], v[170:173], v[34:37]
	v_mfma_f32_16x16x32_bf16 v[26:29], v[154:157], v[170:173], v[26:29]
	v_mfma_f32_16x16x32_bf16 v[18:21], v[146:149], v[178:181], v[18:21]
	v_mfma_f32_16x16x32_bf16 v[10:13], v[154:157], v[178:181], v[10:13]
	v_mfma_f32_16x16x32_bf16 v[6:9], v[146:149], v[186:189], v[6:9]
	v_mfma_f32_16x16x32_bf16 v[2:5], v[154:157], v[186:189], v[2:5]
	v_mfma_f32_16x16x32_bf16 v[50:53], v[150:153], v[166:169], v[50:53]
	v_mfma_f32_16x16x32_bf16 v[42:45], v[158:161], v[166:169], v[42:45]
	v_mfma_f32_16x16x32_bf16 v[34:37], v[150:153], v[174:177], v[34:37]
	v_mfma_f32_16x16x32_bf16 v[26:29], v[158:161], v[174:177], v[26:29]
	v_mfma_f32_16x16x32_bf16 v[18:21], v[150:153], v[182:185], v[18:21]
	v_mfma_f32_16x16x32_bf16 v[10:13], v[158:161], v[182:185], v[10:13]
	v_mfma_f32_16x16x32_bf16 v[6:9], v[150:153], v[190:193], v[6:9]
	v_mfma_f32_16x16x32_bf16 v[2:5], v[158:161], v[190:193], v[2:5]
	s_barrier
; #define PG8_STAGE(bufoff, gbase, voff) do { _Pragma("unroll") for (int _i = 0; _i < 2; ++_i) \
;         __builtin_amdgcn_global_load_lds((const unsigned*)((const char*)(gbase) + (voff)[_i]), (LAS unsigned*)(lds + (bufoff) + ldsw + _i * 8192), 16, 0, 0); } while (0)
; #define PG8_LDA(dst, b, h) do { _Pragma("unroll") for (int m = 0; m < 4; ++m) _Pragma("unroll") for (int k = 0; k < 2; ++k) dst[m][k] = *(const LAS bf16x8*)(lds + PG8_SA(b, h) + aoff + m * 2048 + k * 1024); } while (0)
; #define PG8_LDB(dst, b, h) do { _Pragma("unroll") for (int n = 0; n < 2; ++n) _Pragma("unroll") for (int k = 0; k < 2; ++k) dst[n][k] = *(const LAS bf16x8*)(lds + PG8_SB(b, h) + boff + n * 2048 + k * 1024); } while (0)
; #define PG8_WAIT_V(n) asm volatile("s_waitcnt vmcnt(" #n ")" ::: "memory")
; #define PG8_WAIT_L(n) asm volatile("s_waitcnt lgkmcnt(" #n ")" ::: "memory")
; #define PG8_BAR __builtin_amdgcn_s_barrier()
; #define PG8_SCHED __builtin_amdgcn_sched_barrier(0)
; template <class Epi, class Sched, bool I8 = false>
; __device__ __forceinline__ void gemm_phase(LAS unsigned char* lds, const Gemm g, const Sched& S, const Epi& E) {
;     ...
;             PG8_LDB(B0, 1, 0); PG8_LDB(B1, 1, 1); PG8_SCHED; PG8_LDA(At, 1, 0); PG8_STAGE(PG8_SA(0, 1), a2 + hstepA, voffA);
;             PG8_WAIT_V(8); PG8_WAIT_L(0); PG8_BAR; PG8_MMA(0, 0, At, B0); PG8_MMA(0, 1, At, B1); PG8_BAR; PG8_SCHED;
;             PG8_LDA(At, 1, 1); PG8_STAGE(PG8_SB(1, 0), b3, voffB); PG8_STAGE(PG8_SB(1, 1), b3 + hstepB, voffB); PG8_STAGE(PG8_SA(1, 0), a3, voffA);
;             PG8_WAIT_V(8); PG8_WAIT_L(0); PG8_BAR; PG8_MMA(1, 0, At, B0); PG8_MMA(1, 1, At, B1); PG8_BAR; PG8_SCHED;
;         }
	s_add_i32 s60, 0, 0x18000
	s_add_i32 s61, 0, 0x1c000
	v_add_u32_e32 v142, s60, v230
	v_add_u32_e32 v158, s61, v230
	ds_read_b128 v[130:133], v142
	ds_read_b128 v[134:137], v142 offset:1024
	ds_read_b128 v[138:141], v142 offset:2048
	ds_read_b128 v[142:145], v142 offset:3072
	ds_read_b128 v[146:149], v158
	ds_read_b128 v[150:153], v158 offset:1024
	ds_read_b128 v[154:157], v158 offset:2048
	ds_read_b128 v[158:161], v158 offset:3072
	s_mov_b32 m0, s44
	s_nop 0
	global_load_lds_dwordx4 v194, s[38:39]
	s_mov_b32 m0, s45
	s_nop 0
	global_load_lds_dwordx4 v198, s[38:39]
	s_add_u32 s38, s38, 0x4000
	s_addc_u32 s39, s39, 0
	s_mov_b32 m0, s46
	ds_read_b128 v[162:165], v233 offset:32768
	ds_read_b128 v[166:169], v233 offset:33792
	ds_read_b128 v[170:173], v233 offset:34816
	ds_read_b128 v[174:177], v233 offset:35840
	ds_read_b128 v[178:181], v233 offset:36864
	ds_read_b128 v[182:185], v233 offset:37888
	ds_read_b128 v[186:189], v233 offset:38912
	ds_read_b128 v[190:193], v233 offset:39936
	global_load_lds_dwordx4 v194, s[38:39]
	s_mov_b32 m0, s47
	s_nop 0
	global_load_lds_dwordx4 v198, s[38:39]
	s_waitcnt vmcnt(8)
	s_waitcnt lgkmcnt(0)
	s_barrier
	v_mfma_f32_16x16x32_bf16 v[126:129], v[130:133], v[162:165], v[126:129]
	v_mfma_f32_16x16x32_bf16 v[122:125], v[138:141], v[162:165], v[122:125]
	v_mfma_f32_16x16x32_bf16 v[118:121], v[130:133], v[170:173], v[118:121]
	v_mfma_f32_16x16x32_bf16 v[110:113], v[138:141], v[170:173], v[110:113]
	v_mfma_f32_16x16x32_bf16 v[102:105], v[130:133], v[178:181], v[102:105]
	v_mfma_f32_16x16x32_bf16 v[94:97], v[138:141], v[178:181], v[94:97]
	v_mfma_f32_16x16x32_bf16 v[86:89], v[130:133], v[186:189], v[86:89]
	v_mfma_f32_16x16x32_bf16 v[78:81], v[138:141], v[186:189], v[78:81]
	v_mfma_f32_16x16x32_bf16 v[126:129], v[134:137], v[166:169], v[126:129]
	v_mfma_f32_16x16x32_bf16 v[122:125], v[142:145], v[166:169], v[122:125]
	v_mfma_f32_16x16x32_bf16 v[118:121], v[134:137], v[174:177], v[118:121]
	v_mfma_f32_16x16x32_bf16 v[110:113], v[142:145], v[174:177], v[110:113]
	v_mfma_f32_16x16x32_bf16 v[102:105], v[134:137], v[182:185], v[102:105]
	v_mfma_f32_16x16x32_bf16 v[94:97], v[142:145], v[182:185], v[94:97]
	v_mfma_f32_16x16x32_bf16 v[86:89], v[134:137], v[190:193], v[86:89]
	v_mfma_f32_16x16x32_bf16 v[78:81], v[142:145], v[190:193], v[78:81]
	v_mfma_f32_16x16x32_bf16 v[114:117], v[146:149], v[162:165], v[114:117]
	v_mfma_f32_16x16x32_bf16 v[106:109], v[154:157], v[162:165], v[106:109]
	v_mfma_f32_16x16x32_bf16 v[98:101], v[146:149], v[170:173], v[98:101]
	v_mfma_f32_16x16x32_bf16 v[90:93], v[154:157], v[170:173], v[90:93]
	v_mfma_f32_16x16x32_bf16 v[82:85], v[146:149], v[178:181], v[82:85]
	v_mfma_f32_16x16x32_bf16 v[74:77], v[154:157], v[178:181], v[74:77]
	v_mfma_f32_16x16x32_bf16 v[70:73], v[146:149], v[186:189], v[70:73]
	v_mfma_f32_16x16x32_bf16 v[66:69], v[154:157], v[186:189], v[66:69]
	v_mfma_f32_16x16x32_bf16 v[114:117], v[150:153], v[166:169], v[114:117]
	v_mfma_f32_16x16x32_bf16 v[106:109], v[158:161], v[166:169], v[106:109]
	v_mfma_f32_16x16x32_bf16 v[98:101], v[150:153], v[174:177], v[98:101]
	v_mfma_f32_16x16x32_bf16 v[90:93], v[158:161], v[174:177], v[90:93]
	v_mfma_f32_16x16x32_bf16 v[82:85], v[150:153], v[182:185], v[82:85]
	v_mfma_f32_16x16x32_bf16 v[74:77], v[158:161], v[182:185], v[74:77]
	v_mfma_f32_16x16x32_bf16 v[70:73], v[150:153], v[190:193], v[70:73]
	v_mfma_f32_16x16x32_bf16 v[66:69], v[158:161], v[190:193], v[66:69]
	s_barrier
	s_add_u32 s38, s36, 0x8000
	s_addc_u32 s39, s37, 0
	s_add_i32 s60, s60, s43
	s_mov_b32 m0, s60
	ds_read_b128 v[162:165], v233 offset:49152
	ds_read_b128 v[166:169], v233 offset:50176
	ds_read_b128 v[170:173], v233 offset:51200
	ds_read_b128 v[174:177], v233 offset:52224
	ds_read_b128 v[178:181], v233 offset:53248
	ds_read_b128 v[182:185], v233 offset:54272
	ds_read_b128 v[186:189], v233 offset:55296
	ds_read_b128 v[190:193], v233 offset:56320
	global_load_lds_dwordx4 v196, s[38:39]
	s_add_i32 m0, s60, 0x2000
	s_add_u32 s36, s36, 0xc000
	v_lshl_add_u64 v[212:213], s[38:39], 0, v[200:201]
	s_addc_u32 s37, s37, 0
	s_add_i32 s38, s61, s43
	global_load_lds_dwordx4 v[212:213], off
	s_mov_b32 m0, s38
	s_nop 0
	global_load_lds_dwordx4 v196, s[36:37]
	s_add_i32 m0, s38, 0x2000
	s_nop 0
	global_load_lds_dwordx4 v200, s[36:37]
	s_waitcnt vmcnt(6)
	s_waitcnt lgkmcnt(0)
	s_barrier
	v_mfma_f32_16x16x32_bf16 v[62:65], v[130:133], v[162:165], v[62:65]
	v_mfma_f32_16x16x32_bf16 v[58:61], v[138:141], v[162:165], v[58:61]
	v_mfma_f32_16x16x32_bf16 v[54:57], v[130:133], v[170:173], v[54:57]
	v_mfma_f32_16x16x32_bf16 v[46:49], v[138:141], v[170:173], v[46:49]
	v_mfma_f32_16x16x32_bf16 v[38:41], v[130:133], v[178:181], v[38:41]
	v_mfma_f32_16x16x32_bf16 v[30:33], v[138:141], v[178:181], v[30:33]
	v_mfma_f32_16x16x32_bf16 v[22:25], v[130:133], v[186:189], v[22:25]
	v_mfma_f32_16x16x32_bf16 v[14:17], v[138:141], v[186:189], v[14:17]
	v_mfma_f32_16x16x32_bf16 v[62:65], v[134:137], v[166:169], v[62:65]
	v_mfma_f32_16x16x32_bf16 v[58:61], v[142:145], v[166:169], v[58:61]
	v_mfma_f32_16x16x32_bf16 v[54:57], v[134:137], v[174:177], v[54:57]
	v_mfma_f32_16x16x32_bf16 v[46:49], v[142:145], v[174:177], v[46:49]
	v_mfma_f32_16x16x32_bf16 v[38:41], v[134:137], v[182:185], v[38:41]
	v_mfma_f32_16x16x32_bf16 v[30:33], v[142:145], v[182:185], v[30:33]
	v_mfma_f32_16x16x32_bf16 v[22:25], v[134:137], v[190:193], v[22:25]
	v_mfma_f32_16x16x32_bf16 v[14:17], v[142:145], v[190:193], v[14:17]
	v_mfma_f32_16x16x32_bf16 v[50:53], v[146:149], v[162:165], v[50:53]
	v_mfma_f32_16x16x32_bf16 v[42:45], v[154:157], v[162:165], v[42:45]
	v_mfma_f32_16x16x32_bf16 v[34:37], v[146:149], v[170:173], v[34:37]
	v_mfma_f32_16x16x32_bf16 v[26:29], v[154:157], v[170:173], v[26:29]
	v_mfma_f32_16x16x32_bf16 v[18:21], v[146:149], v[178:181], v[18:21]
	v_mfma_f32_16x16x32_bf16 v[10:13], v[154:157], v[178:181], v[10:13]
	v_mfma_f32_16x16x32_bf16 v[6:9], v[146:149], v[186:189], v[6:9]
	v_mfma_f32_16x16x32_bf16 v[2:5], v[154:157], v[186:189], v[2:5]
	v_mfma_f32_16x16x32_bf16 v[50:53], v[150:153], v[166:169], v[50:53]
	v_mfma_f32_16x16x32_bf16 v[42:45], v[158:161], v[166:169], v[42:45]
	v_mfma_f32_16x16x32_bf16 v[34:37], v[150:153], v[174:177], v[34:37]
	v_mfma_f32_16x16x32_bf16 v[26:29], v[158:161], v[174:177], v[26:29]
	v_mfma_f32_16x16x32_bf16 v[18:21], v[150:153], v[182:185], v[18:21]
	v_mfma_f32_16x16x32_bf16 v[10:13], v[158:161], v[182:185], v[10:13]
	v_mfma_f32_16x16x32_bf16 v[6:9], v[150:153], v[190:193], v[6:9]
	v_mfma_f32_16x16x32_bf16 v[2:5], v[158:161], v[190:193], v[2:5]
	s_barrier
	s_add_i32 s59, s59, 2
	s_add_u32 s30, s30, 0x10000
	s_addc_u32 s31, s31, 0
	s_add_u32 s57, s57, 0x10000
	s_addc_u32 s58, s58, 0
	s_cmp_gt_u32 s59, 61
	s_cbranch_scc0 .LBB0_3744
	s_and_b64 vcc, exec, s[6:7]
	s_cbranch_vccz .LBB0_3747
	s_barrier

; #define PG8_STAGE(bufoff, gbase, voff) do { _Pragma("unroll") for (int _i = 0; _i < 2; ++_i) \
;         __builtin_amdgcn_global_load_lds((const unsigned*)((const char*)(gbase) + (voff)[_i]), (LAS unsigned*)(lds + (bufoff) + ldsw + _i * 8192), 16, 0, 0); } while (0)
; #define PG8_LDA(dst, b, h) do { _Pragma("unroll") for (int m = 0; m < 4; ++m) _Pragma("unroll") for (int k = 0; k < 2; ++k) dst[m][k] = *(const LAS bf16x8*)(lds + PG8_SA(b, h) + aoff + m * 2048 + k * 1024); } while (0)
; #define PG8_LDB(dst, b, h) do { _Pragma("unroll") for (int n = 0; n < 2; ++n) _Pragma("unroll") for (int k = 0; k < 2; ++k) dst[n][k] = *(const LAS bf16x8*)(lds + PG8_SB(b, h) + boff + n * 2048 + k * 1024); } while (0)
; #define PG8_WAIT_V(n) asm volatile("s_waitcnt vmcnt(" #n ")" ::: "memory")
; #define PG8_WAIT_L(n) asm volatile("s_waitcnt lgkmcnt(" #n ")" ::: "memory")
; #define PG8_BAR __builtin_amdgcn_s_barrier()
; #define PG8_SCHED __builtin_amdgcn_sched_barrier(0)
; template <class Epi, class Sched, bool I8 = false>
; __device__ __forceinline__ void gemm_phase(LAS unsigned char* lds, const Gemm g, const Sched& S, const Epi& E) {
;     ...
;             const bool last = (t == nt - 2);
;             const char* a1 = cA + (size_t)(t + 1) * kstep;
;             const char* a2 = last ? nA : cA + (size_t)(t + 2) * kstep; const char* b2 = last ? nB : cB + (size_t)(t + 2) * kstep;
;             const char* a3 = a2 + kstep; const char* b3 = b2 + kstep;
;             PG8_LDB(B0, 0, 0); PG8_LDB(B1, 0, 1); PG8_SCHED; PG8_LDA(At, 0, 0); PG8_STAGE(PG8_SA(1, 1), a1 + hstepA, voffA);
;             PG8_WAIT_V(8); PG8_WAIT_L(0); PG8_BAR; PG8_MMA(0, 0, At, B0); PG8_MMA(0, 1, At, B1); PG8_BAR; PG8_SCHED;
;             PG8_LDA(At, 0, 1); PG8_STAGE(PG8_SB(0, 0), b2, voffB); PG8_STAGE(PG8_SB(0, 1), b2 + hstepB, voffB); PG8_STAGE(PG8_SA(0, 0), a2, voffA);
;             PG8_WAIT_V(8); PG8_WAIT_L(0); PG8_BAR; PG8_MMA(1, 0, At, B0); PG8_MMA(1, 1, At, B1); PG8_BAR; PG8_SCHED;
.LBB0_4168:
	ds_read_b128 v[66:69], v178
	ds_read_b128 v[70:73], v178 offset:1024
	ds_read_b128 v[74:77], v178 offset:2048
	ds_read_b128 v[78:81], v178 offset:3072
	ds_read_b128 v[146:149], v179
	ds_read_b128 v[150:153], v179 offset:1024
	ds_read_b128 v[172:175], v179 offset:2048
	ds_read_b128 v[182:185], v179 offset:3072
	s_add_u32 s22, s20, 0x4000
	s_addc_u32 s23, s21, 0
	s_cmpk_eq_i32 s51, 0x52
	s_cselect_b32 s26, s0, s22
	s_cselect_b32 s27, s1, s23
	s_cselect_b32 s24, s18, s49
	s_cselect_b32 s25, s19, s50
	s_add_u32 s22, s26, 0x8000
	s_addc_u32 s23, s27, 0
	s_sub_u32 s98, s20, 0x4000
	s_subb_u32 s99, s21, 0
	s_mov_b32 m0, s39
	s_nop 0
	global_load_lds_dwordx4 v154, s[98:99]
	s_mov_b32 m0, s40
	s_nop 0
	global_load_lds_dwordx4 v158, s[98:99]
	s_add_i32 m0, s34, 0xc000
	ds_read_b128 v[186:189], v180
	ds_read_b128 v[190:193], v180 offset:1024
	ds_read_b128 v[194:197], v180 offset:2048
	ds_read_b128 v[198:201], v180 offset:3072
	ds_read_b128 v[202:205], v180 offset:4096
	ds_read_b128 v[206:209], v180 offset:5120
	ds_read_b128 v[210:213], v180 offset:6144
	ds_read_b128 v[214:217], v180 offset:7168
	global_load_lds_dwordx4 v164, s[20:21]
	s_add_i32 m0, s34, 0xe000
	s_nop 0
	global_load_lds_dwordx4 v166, s[20:21]
	s_waitcnt vmcnt(8)
	s_waitcnt lgkmcnt(0)
	s_barrier
	v_mfma_i32_16x16x64_i8 v[142:145], v[66:69], v[186:189], v[142:145]
	v_mfma_i32_16x16x64_i8 v[138:141], v[74:77], v[186:189], v[138:141]
	v_mfma_i32_16x16x64_i8 v[126:129], v[66:69], v[194:197], v[126:129]
	v_mfma_i32_16x16x64_i8 v[122:125], v[74:77], v[194:197], v[122:125]
	v_mfma_i32_16x16x64_i8 v[110:113], v[66:69], v[202:205], v[110:113]
	v_mfma_i32_16x16x64_i8 v[106:109], v[74:77], v[202:205], v[106:109]
	v_mfma_i32_16x16x64_i8 v[94:97], v[66:69], v[210:213], v[94:97]
	v_mfma_i32_16x16x64_i8 v[90:93], v[74:77], v[210:213], v[90:93]
	v_mfma_i32_16x16x64_i8 v[142:145], v[70:73], v[190:193], v[142:145]
	v_mfma_i32_16x16x64_i8 v[138:141], v[78:81], v[190:193], v[138:141]
	v_mfma_i32_16x16x64_i8 v[126:129], v[70:73], v[198:201], v[126:129]
	v_mfma_i32_16x16x64_i8 v[122:125], v[78:81], v[198:201], v[122:125]
	v_mfma_i32_16x16x64_i8 v[110:113], v[70:73], v[206:209], v[110:113]
	v_mfma_i32_16x16x64_i8 v[106:109], v[78:81], v[206:209], v[106:109]
	v_mfma_i32_16x16x64_i8 v[94:97], v[70:73], v[214:217], v[94:97]
	v_mfma_i32_16x16x64_i8 v[90:93], v[78:81], v[214:217], v[90:93]
	v_mfma_i32_16x16x64_i8 v[134:137], v[146:149], v[186:189], v[134:137]
	v_mfma_i32_16x16x64_i8 v[130:133], v[172:175], v[186:189], v[130:133]
	v_mfma_i32_16x16x64_i8 v[118:121], v[146:149], v[194:197], v[118:121]
	v_mfma_i32_16x16x64_i8 v[114:117], v[172:175], v[194:197], v[114:117]
	v_mfma_i32_16x16x64_i8 v[102:105], v[146:149], v[202:205], v[102:105]
	v_mfma_i32_16x16x64_i8 v[98:101], v[172:175], v[202:205], v[98:101]
	v_mfma_i32_16x16x64_i8 v[86:89], v[146:149], v[210:213], v[86:89]
	v_mfma_i32_16x16x64_i8 v[82:85], v[172:175], v[210:213], v[82:85]
	v_mfma_i32_16x16x64_i8 v[134:137], v[150:153], v[190:193], v[134:137]
	v_mfma_i32_16x16x64_i8 v[130:133], v[182:185], v[190:193], v[130:133]
	v_mfma_i32_16x16x64_i8 v[118:121], v[150:153], v[198:201], v[118:121]
	v_mfma_i32_16x16x64_i8 v[114:117], v[182:185], v[198:201], v[114:117]
	v_mfma_i32_16x16x64_i8 v[102:105], v[150:153], v[206:209], v[102:105]
	v_mfma_i32_16x16x64_i8 v[98:101], v[182:185], v[206:209], v[98:101]
	v_mfma_i32_16x16x64_i8 v[86:89], v[150:153], v[214:217], v[86:89]
	v_mfma_i32_16x16x64_i8 v[82:85], v[182:185], v[214:217], v[82:85]
	s_barrier
	s_add_i32 s52, s43, s33
	s_mov_b32 m0, s52
	ds_read_b128 v[186:189], v180 offset:16384
	ds_read_b128 v[190:193], v180 offset:17408
	ds_read_b128 v[194:197], v180 offset:18432
	ds_read_b128 v[198:201], v180 offset:19456
	ds_read_b128 v[202:205], v180 offset:20480
	ds_read_b128 v[206:209], v180 offset:21504
	ds_read_b128 v[210:213], v180 offset:22528
	ds_read_b128 v[214:217], v180 offset:23552
	global_load_lds_dwordx4 v156, s[24:25]
	s_add_i32 m0, s52, 0x2000
	s_add_u32 s52, s24, 0x4000
	s_addc_u32 s53, s25, 0
	s_add_i32 s54, s44, s33
	global_load_lds_dwordx4 v160, s[24:25]
	s_mov_b32 m0, s54
	s_nop 0
	global_load_lds_dwordx4 v156, s[52:53]
	s_add_i32 m0, s54, 0x2000
	s_nop 0
	global_load_lds_dwordx4 v160, s[52:53]
	s_waitcnt vmcnt(6)
	s_waitcnt lgkmcnt(0)
	s_barrier
	v_mfma_i32_16x16x64_i8 v[62:65], v[66:69], v[186:189], v[62:65]
	v_mfma_i32_16x16x64_i8 v[58:61], v[74:77], v[186:189], v[58:61]
	v_mfma_i32_16x16x64_i8 v[46:49], v[66:69], v[194:197], v[46:49]
	v_mfma_i32_16x16x64_i8 v[42:45], v[74:77], v[194:197], v[42:45]
	v_mfma_i32_16x16x64_i8 v[30:33], v[66:69], v[202:205], v[30:33]
	v_mfma_i32_16x16x64_i8 v[26:29], v[74:77], v[202:205], v[26:29]
	v_mfma_i32_16x16x64_i8 v[14:17], v[66:69], v[210:213], v[14:17]
	v_mfma_i32_16x16x64_i8 v[10:13], v[74:77], v[210:213], v[10:13]
	v_mfma_i32_16x16x64_i8 v[62:65], v[70:73], v[190:193], v[62:65]
	v_mfma_i32_16x16x64_i8 v[58:61], v[78:81], v[190:193], v[58:61]
	v_mfma_i32_16x16x64_i8 v[46:49], v[70:73], v[198:201], v[46:49]
	v_mfma_i32_16x16x64_i8 v[42:45], v[78:81], v[198:201], v[42:45]
	v_mfma_i32_16x16x64_i8 v[30:33], v[70:73], v[206:209], v[30:33]
	v_mfma_i32_16x16x64_i8 v[26:29], v[78:81], v[206:209], v[26:29]
	v_mfma_i32_16x16x64_i8 v[14:17], v[70:73], v[214:217], v[14:17]
	v_mfma_i32_16x16x64_i8 v[10:13], v[78:81], v[214:217], v[10:13]
	v_mfma_i32_16x16x64_i8 v[54:57], v[146:149], v[186:189], v[54:57]
	v_mfma_i32_16x16x64_i8 v[50:53], v[172:175], v[186:189], v[50:53]
	v_mfma_i32_16x16x64_i8 v[38:41], v[146:149], v[194:197], v[38:41]
	v_mfma_i32_16x16x64_i8 v[34:37], v[172:175], v[194:197], v[34:37]
	v_mfma_i32_16x16x64_i8 v[22:25], v[146:149], v[202:205], v[22:25]
	v_mfma_i32_16x16x64_i8 v[18:21], v[172:175], v[202:205], v[18:21]
	v_mfma_i32_16x16x64_i8 v[6:9], v[146:149], v[210:213], v[6:9]
	v_mfma_i32_16x16x64_i8 v[2:5], v[172:175], v[210:213], v[2:5]
	v_mfma_i32_16x16x64_i8 v[54:57], v[150:153], v[190:193], v[54:57]
	v_mfma_i32_16x16x64_i8 v[50:53], v[182:185], v[190:193], v[50:53]
	v_mfma_i32_16x16x64_i8 v[38:41], v[150:153], v[198:201], v[38:41]
	v_mfma_i32_16x16x64_i8 v[34:37], v[182:185], v[198:201], v[34:37]
	v_mfma_i32_16x16x64_i8 v[22:25], v[150:153], v[206:209], v[22:25]
	v_mfma_i32_16x16x64_i8 v[18:21], v[182:185], v[206:209], v[18:21]
	v_mfma_i32_16x16x64_i8 v[6:9], v[150:153], v[214:217], v[6:9]
	v_mfma_i32_16x16x64_i8 v[2:5], v[182:185], v[214:217], v[2:5]
	s_barrier
; #define PG8_STAGE(bufoff, gbase, voff) do { _Pragma("unroll") for (int _i = 0; _i < 2; ++_i) \
;         __builtin_amdgcn_global_load_lds((const unsigned*)((const char*)(gbase) + (voff)[_i]), (LAS unsigned*)(lds + (bufoff) + ldsw + _i * 8192), 16, 0, 0); } while (0)
; #define PG8_LDA(dst, b, h) do { _Pragma("unroll") for (int m = 0; m < 4; ++m) _Pragma("unroll") for (int k = 0; k < 2; ++k) dst[m][k] = *(const LAS bf16x8*)(lds + PG8_SA(b, h) + aoff + m * 2048 + k * 1024); } while (0)
; #define PG8_LDB(dst, b, h) do { _Pragma("unroll") for (int n = 0; n < 2; ++n) _Pragma("unroll") for (int k = 0; k < 2; ++k) dst[n][k] = *(const LAS bf16x8*)(lds + PG8_SB(b, h) + boff + n * 2048 + k * 1024); } while (0)
; #define PG8_WAIT_V(n) asm volatile("s_waitcnt vmcnt(" #n ")" ::: "memory")
; #define PG8_WAIT_L(n) asm volatile("s_waitcnt lgkmcnt(" #n ")" ::: "memory")
; #define PG8_BAR __builtin_amdgcn_s_barrier()
; #define PG8_SCHED __builtin_amdgcn_sched_barrier(0)
; template <class Epi, class Sched, bool I8 = false>
; __device__ __forceinline__ void gemm_phase(LAS unsigned char* lds, const Gemm g, const Sched& S, const Epi& E) {
;     ...
;             PG8_LDB(B0, 1, 0); PG8_LDB(B1, 1, 1); PG8_SCHED; PG8_LDA(At, 1, 0); PG8_STAGE(PG8_SA(0, 1), a2 + hstepA, voffA);
;             PG8_WAIT_V(8); PG8_WAIT_L(0); PG8_BAR; PG8_MMA(0, 0, At, B0); PG8_MMA(0, 1, At, B1); PG8_BAR; PG8_SCHED;
;             PG8_LDA(At, 1, 1); PG8_STAGE(PG8_SB(1, 0), b3, voffB); PG8_STAGE(PG8_SB(1, 1), b3 + hstepB, voffB); PG8_STAGE(PG8_SA(1, 0), a3, voffA);
;             PG8_WAIT_V(8); PG8_WAIT_L(0); PG8_BAR; PG8_MMA(1, 0, At, B0); PG8_MMA(1, 1, At, B1); PG8_BAR; PG8_SCHED;
;         }
	s_add_i32 s52, 0, 0x18000
	s_add_i32 s53, 0, 0x1c000
	v_add_u32_e32 v78, s52, v176
	v_add_u32_e32 v162, s53, v176
	ds_read_b128 v[66:69], v78
	ds_read_b128 v[70:73], v78 offset:1024
	ds_read_b128 v[74:77], v78 offset:2048
	ds_read_b128 v[78:81], v78 offset:3072
	ds_read_b128 v[146:149], v162
	ds_read_b128 v[150:153], v162 offset:1024
	ds_read_b128 v[172:175], v162 offset:2048
	ds_read_b128 v[182:185], v162 offset:3072
	s_mov_b32 m0, s34
	s_nop 0
	global_load_lds_dwordx4 v154, s[26:27]
	s_mov_b32 m0, s35
	s_nop 0
	global_load_lds_dwordx4 v158, s[26:27]
	s_add_u32 s26, s26, 0x4000
	s_addc_u32 s27, s27, 0
	s_mov_b32 m0, s36
	ds_read_b128 v[186:189], v180 offset:32768
	ds_read_b128 v[190:193], v180 offset:33792
	ds_read_b128 v[194:197], v180 offset:34816
	ds_read_b128 v[198:201], v180 offset:35840
	ds_read_b128 v[202:205], v180 offset:36864
	ds_read_b128 v[206:209], v180 offset:37888
	ds_read_b128 v[210:213], v180 offset:38912
	ds_read_b128 v[214:217], v180 offset:39936
	global_load_lds_dwordx4 v154, s[26:27]
	s_mov_b32 m0, s37
	s_nop 0
	global_load_lds_dwordx4 v158, s[26:27]
	s_waitcnt vmcnt(8)
	s_waitcnt lgkmcnt(0)
	s_barrier
	v_mfma_i32_16x16x64_i8 v[142:145], v[66:69], v[186:189], v[142:145]
	v_mfma_i32_16x16x64_i8 v[138:141], v[74:77], v[186:189], v[138:141]
	v_mfma_i32_16x16x64_i8 v[126:129], v[66:69], v[194:197], v[126:129]
	v_mfma_i32_16x16x64_i8 v[122:125], v[74:77], v[194:197], v[122:125]
	v_mfma_i32_16x16x64_i8 v[110:113], v[66:69], v[202:205], v[110:113]
	v_mfma_i32_16x16x64_i8 v[106:109], v[74:77], v[202:205], v[106:109]
	v_mfma_i32_16x16x64_i8 v[94:97], v[66:69], v[210:213], v[94:97]
	v_mfma_i32_16x16x64_i8 v[90:93], v[74:77], v[210:213], v[90:93]
	v_mfma_i32_16x16x64_i8 v[142:145], v[70:73], v[190:193], v[142:145]
	v_mfma_i32_16x16x64_i8 v[138:141], v[78:81], v[190:193], v[138:141]
	v_mfma_i32_16x16x64_i8 v[126:129], v[70:73], v[198:201], v[126:129]
	v_mfma_i32_16x16x64_i8 v[122:125], v[78:81], v[198:201], v[122:125]
	v_mfma_i32_16x16x64_i8 v[110:113], v[70:73], v[206:209], v[110:113]
	v_mfma_i32_16x16x64_i8 v[106:109], v[78:81], v[206:209], v[106:109]
	v_mfma_i32_16x16x64_i8 v[94:97], v[70:73], v[214:217], v[94:97]
	v_mfma_i32_16x16x64_i8 v[90:93], v[78:81], v[214:217], v[90:93]
	v_mfma_i32_16x16x64_i8 v[134:137], v[146:149], v[186:189], v[134:137]
	v_mfma_i32_16x16x64_i8 v[130:133], v[172:175], v[186:189], v[130:133]
	v_mfma_i32_16x16x64_i8 v[118:121], v[146:149], v[194:197], v[118:121]
	v_mfma_i32_16x16x64_i8 v[114:117], v[172:175], v[194:197], v[114:117]
	v_mfma_i32_16x16x64_i8 v[102:105], v[146:149], v[202:205], v[102:105]
	v_mfma_i32_16x16x64_i8 v[98:101], v[172:175], v[202:205], v[98:101]
	v_mfma_i32_16x16x64_i8 v[86:89], v[146:149], v[210:213], v[86:89]
	v_mfma_i32_16x16x64_i8 v[82:85], v[172:175], v[210:213], v[82:85]
	v_mfma_i32_16x16x64_i8 v[134:137], v[150:153], v[190:193], v[134:137]
	v_mfma_i32_16x16x64_i8 v[130:133], v[182:185], v[190:193], v[130:133]
	v_mfma_i32_16x16x64_i8 v[118:121], v[150:153], v[198:201], v[118:121]
	v_mfma_i32_16x16x64_i8 v[114:117], v[182:185], v[198:201], v[114:117]
	v_mfma_i32_16x16x64_i8 v[102:105], v[150:153], v[206:209], v[102:105]
	v_mfma_i32_16x16x64_i8 v[98:101], v[182:185], v[206:209], v[98:101]
	v_mfma_i32_16x16x64_i8 v[86:89], v[150:153], v[214:217], v[86:89]
	v_mfma_i32_16x16x64_i8 v[82:85], v[182:185], v[214:217], v[82:85]
	s_barrier
	s_add_u32 s26, s24, 0x8000
	s_addc_u32 s27, s25, 0
	s_add_i32 s52, s52, s33
	s_mov_b32 m0, s52
	ds_read_b128 v[186:189], v180 offset:49152
	ds_read_b128 v[190:193], v180 offset:50176
	ds_read_b128 v[194:197], v180 offset:51200
	ds_read_b128 v[198:201], v180 offset:52224
	ds_read_b128 v[202:205], v180 offset:53248
	ds_read_b128 v[206:209], v180 offset:54272
	ds_read_b128 v[210:213], v180 offset:55296
	ds_read_b128 v[214:217], v180 offset:56320
	global_load_lds_dwordx4 v156, s[26:27]
	s_add_i32 m0, s52, 0x2000
	s_add_u32 s24, s24, 0xc000
	v_lshl_add_u64 v[218:219], s[26:27], 0, v[160:161]
	s_addc_u32 s25, s25, 0
	s_add_i32 s26, s53, s33
	global_load_lds_dwordx4 v[218:219], off
	s_mov_b32 m0, s26
	s_nop 0
	global_load_lds_dwordx4 v156, s[24:25]
	s_add_i32 m0, s26, 0x2000
	s_nop 0
	global_load_lds_dwordx4 v160, s[24:25]
	s_waitcnt vmcnt(6)
	s_waitcnt lgkmcnt(0)
	s_barrier
	v_mfma_i32_16x16x64_i8 v[62:65], v[66:69], v[186:189], v[62:65]
	v_mfma_i32_16x16x64_i8 v[58:61], v[74:77], v[186:189], v[58:61]
	v_mfma_i32_16x16x64_i8 v[46:49], v[66:69], v[194:197], v[46:49]
	v_mfma_i32_16x16x64_i8 v[42:45], v[74:77], v[194:197], v[42:45]
	v_mfma_i32_16x16x64_i8 v[30:33], v[66:69], v[202:205], v[30:33]
	v_mfma_i32_16x16x64_i8 v[26:29], v[74:77], v[202:205], v[26:29]
	v_mfma_i32_16x16x64_i8 v[14:17], v[66:69], v[210:213], v[14:17]
	v_mfma_i32_16x16x64_i8 v[10:13], v[74:77], v[210:213], v[10:13]
	v_mfma_i32_16x16x64_i8 v[62:65], v[70:73], v[190:193], v[62:65]
	v_mfma_i32_16x16x64_i8 v[58:61], v[78:81], v[190:193], v[58:61]
	v_mfma_i32_16x16x64_i8 v[46:49], v[70:73], v[198:201], v[46:49]
	v_mfma_i32_16x16x64_i8 v[42:45], v[78:81], v[198:201], v[42:45]
	v_mfma_i32_16x16x64_i8 v[30:33], v[70:73], v[206:209], v[30:33]
	v_mfma_i32_16x16x64_i8 v[26:29], v[78:81], v[206:209], v[26:29]
	v_mfma_i32_16x16x64_i8 v[14:17], v[70:73], v[214:217], v[14:17]
	v_mfma_i32_16x16x64_i8 v[10:13], v[78:81], v[214:217], v[10:13]
	v_mfma_i32_16x16x64_i8 v[54:57], v[146:149], v[186:189], v[54:57]
	v_mfma_i32_16x16x64_i8 v[50:53], v[172:175], v[186:189], v[50:53]
	v_mfma_i32_16x16x64_i8 v[38:41], v[146:149], v[194:197], v[38:41]
	v_mfma_i32_16x16x64_i8 v[34:37], v[172:175], v[194:197], v[34:37]
	v_mfma_i32_16x16x64_i8 v[22:25], v[146:149], v[202:205], v[22:25]
	v_mfma_i32_16x16x64_i8 v[18:21], v[172:175], v[202:205], v[18:21]
	v_mfma_i32_16x16x64_i8 v[6:9], v[146:149], v[210:213], v[6:9]
	v_mfma_i32_16x16x64_i8 v[2:5], v[172:175], v[210:213], v[2:5]
	v_mfma_i32_16x16x64_i8 v[54:57], v[150:153], v[190:193], v[54:57]
	v_mfma_i32_16x16x64_i8 v[50:53], v[182:185], v[190:193], v[50:53]
	v_mfma_i32_16x16x64_i8 v[38:41], v[150:153], v[198:201], v[38:41]
	v_mfma_i32_16x16x64_i8 v[34:37], v[182:185], v[198:201], v[34:37]
	v_mfma_i32_16x16x64_i8 v[22:25], v[150:153], v[206:209], v[22:25]
	v_mfma_i32_16x16x64_i8 v[18:21], v[182:185], v[206:209], v[18:21]
	v_mfma_i32_16x16x64_i8 v[6:9], v[150:153], v[214:217], v[6:9]
	v_mfma_i32_16x16x64_i8 v[2:5], v[182:185], v[214:217], v[2:5]
	s_barrier
	s_add_i32 s51, s51, 2
	s_add_u32 s20, s20, 0x10000
	s_addc_u32 s21, s21, 0
	s_add_u32 s49, s49, 0x10000
	s_addc_u32 s50, s50, 0
	s_cmpk_gt_u32 s51, 0x53
	s_cbranch_scc0 .LBB0_4168
	s_and_b64 vcc, exec, s[14:15]
	s_cbranch_vccz .LBB0_4171
	s_barrier
